# E9+E10: drop dead setprio 0/1 pairs inside MFMA blocks; skinny row_exchange counter arrivals 256->64 (only publishing waves arrive)
# speedup vs baseline: 1.0300x; 1.0044x over previous
.LBB0_202:
	ds_read_b128 v[146:149], v157
	ds_read_b128 v[150:153], v157 offset:1024
	ds_read_b128 v[164:167], v157 offset:2048
	ds_read_b128 v[168:171], v157 offset:3072
	ds_read_b128 v[172:175], v158
	ds_read_b128 v[176:179], v158 offset:1024
	ds_read_b128 v[180:183], v158 offset:2048
	ds_read_b128 v[184:187], v158 offset:3072
	s_add_u32 s72, s76, 0xfffc0080
	s_addc_u32 s73, s77, -1
	s_cmp_eq_u32 s71, 12
	s_cselect_b32 s85, s5, s73
	s_cselect_b32 s84, s43, s72
	s_cselect_b32 s79, s41, s70
	s_cselect_b32 s78, s49, s69
	v_lshl_add_u64 v[188:189], s[76:77], 0, v[138:139]
	s_add_i32 m0, s93, 0xc000
	ds_read_b128 v[192:195], v159
	ds_read_b128 v[196:199], v159 offset:1024
	ds_read_b128 v[200:203], v159 offset:2048
	ds_read_b128 v[204:207], v159 offset:3072
	ds_read_b128 v[208:211], v159 offset:4096
	ds_read_b128 v[218:221], v159 offset:5120
	ds_read_b128 v[224:227], v159 offset:6144
	ds_read_b128 v[228:231], v159 offset:7168
	global_load_lds_dwordx4 v[188:189], off
	v_lshl_add_u64 v[188:189], s[76:77], 0, v[140:141]
	s_add_i32 m0, s93, 0xe000
	s_nop 0
	global_load_lds_dwordx4 v[188:189], off
	s_waitcnt vmcnt(8)
	s_waitcnt lgkmcnt(0)
	s_barrier
	s_setprio 1
	s_waitcnt lgkmcnt(0)
	v_mfma_f32_16x16x32_bf16 v[126:129], v[146:149], v[192:195], v[126:129]
	v_mfma_f32_16x16x32_bf16 v[122:125], v[164:167], v[192:195], v[122:125]
	v_mfma_f32_16x16x32_bf16 v[110:113], v[146:149], v[200:203], v[110:113]
	v_mfma_f32_16x16x32_bf16 v[106:109], v[164:167], v[200:203], v[106:109]
	v_mfma_f32_16x16x32_bf16 v[94:97], v[146:149], v[208:211], v[94:97]
	v_mfma_f32_16x16x32_bf16 v[90:93], v[164:167], v[208:211], v[90:93]
	v_mfma_f32_16x16x32_bf16 v[78:81], v[146:149], v[224:227], v[78:81]
	v_mfma_f32_16x16x32_bf16 v[74:77], v[164:167], v[224:227], v[74:77]
	v_mfma_f32_16x16x32_bf16 v[126:129], v[150:153], v[196:199], v[126:129]
	v_mfma_f32_16x16x32_bf16 v[122:125], v[168:171], v[196:199], v[122:125]
	v_mfma_f32_16x16x32_bf16 v[110:113], v[150:153], v[204:207], v[110:113]
	v_mfma_f32_16x16x32_bf16 v[106:109], v[168:171], v[204:207], v[106:109]
	v_mfma_f32_16x16x32_bf16 v[94:97], v[150:153], v[218:221], v[94:97]
	v_mfma_f32_16x16x32_bf16 v[90:93], v[168:171], v[218:221], v[90:93]
	v_mfma_f32_16x16x32_bf16 v[78:81], v[150:153], v[228:231], v[78:81]
	v_mfma_f32_16x16x32_bf16 v[74:77], v[168:171], v[228:231], v[74:77]
	v_mfma_f32_16x16x32_bf16 v[118:121], v[172:175], v[192:195], v[118:121]
	v_mfma_f32_16x16x32_bf16 v[114:117], v[180:183], v[192:195], v[114:117]
	v_mfma_f32_16x16x32_bf16 v[102:105], v[172:175], v[200:203], v[102:105]
	v_mfma_f32_16x16x32_bf16 v[98:101], v[180:183], v[200:203], v[98:101]
	v_mfma_f32_16x16x32_bf16 v[86:89], v[172:175], v[208:211], v[86:89]
	v_mfma_f32_16x16x32_bf16 v[82:85], v[180:183], v[208:211], v[82:85]
	v_mfma_f32_16x16x32_bf16 v[70:73], v[172:175], v[224:227], v[70:73]
	v_mfma_f32_16x16x32_bf16 v[66:69], v[180:183], v[224:227], v[66:69]
	v_mfma_f32_16x16x32_bf16 v[118:121], v[176:179], v[196:199], v[118:121]
	v_mfma_f32_16x16x32_bf16 v[114:117], v[184:187], v[196:199], v[114:117]
	v_mfma_f32_16x16x32_bf16 v[102:105], v[176:179], v[204:207], v[102:105]
	v_mfma_f32_16x16x32_bf16 v[98:101], v[184:187], v[204:207], v[98:101]
	v_mfma_f32_16x16x32_bf16 v[86:89], v[176:179], v[218:221], v[86:89]
	v_mfma_f32_16x16x32_bf16 v[82:85], v[184:187], v[218:221], v[82:85]
	v_mfma_f32_16x16x32_bf16 v[70:73], v[176:179], v[228:231], v[70:73]
	v_mfma_f32_16x16x32_bf16 v[66:69], v[184:187], v[228:231], v[66:69]
	s_setprio 0
	s_barrier
	s_add_i32 s72, s67, s92
	v_lshl_add_u64 v[188:189], s[78:79], 0, v[132:133]
	s_mov_b32 m0, s72
	ds_read_b128 v[192:195], v159 offset:16384
	ds_read_b128 v[196:199], v159 offset:17408
	ds_read_b128 v[200:203], v159 offset:18432
	ds_read_b128 v[204:207], v159 offset:19456
	ds_read_b128 v[208:211], v159 offset:20480
	ds_read_b128 v[218:221], v159 offset:21504
	ds_read_b128 v[224:227], v159 offset:22528
	ds_read_b128 v[228:231], v159 offset:23552
	global_load_lds_dwordx4 v[188:189], off
	s_add_i32 m0, s72, 0x2000
	s_add_u32 s72, s78, 0x40000
	v_lshl_add_u64 v[214:215], s[78:79], 0, v[136:137]
	s_addc_u32 s73, s79, 0
	s_add_i32 s74, s68, s92
	global_load_lds_dwordx4 v[214:215], off
	v_lshl_add_u64 v[232:233], s[72:73], 0, v[132:133]
	s_mov_b32 m0, s74
	v_lshl_add_u64 v[234:235], s[84:85], 0, v[134:135]
	global_load_lds_dwordx4 v[232:233], off
	v_lshl_add_u64 v[232:233], s[72:73], 0, v[136:137]
	s_add_i32 m0, s74, 0x2000
	s_nop 0
	global_load_lds_dwordx4 v[232:233], off
	v_lshl_add_u64 v[232:233], s[84:85], 0, v[130:131]
	s_mov_b32 m0, s93
	s_nop 0
	global_load_lds_dwordx4 v[232:233], off
	s_mov_b32 m0, s94
	s_nop 0
	global_load_lds_dwordx4 v[234:235], off
	s_waitcnt vmcnt(8)
	s_waitcnt lgkmcnt(0)
	s_barrier
	s_setprio 1
	s_waitcnt lgkmcnt(0)
	v_mfma_f32_16x16x32_bf16 v[62:65], v[146:149], v[192:195], v[62:65]
	v_mfma_f32_16x16x32_bf16 v[58:61], v[164:167], v[192:195], v[58:61]
	v_mfma_f32_16x16x32_bf16 v[46:49], v[146:149], v[200:203], v[46:49]
	v_mfma_f32_16x16x32_bf16 v[42:45], v[164:167], v[200:203], v[42:45]
	v_mfma_f32_16x16x32_bf16 v[30:33], v[146:149], v[208:211], v[30:33]
	v_mfma_f32_16x16x32_bf16 v[26:29], v[164:167], v[208:211], v[26:29]
	v_mfma_f32_16x16x32_bf16 v[14:17], v[146:149], v[224:227], v[14:17]
	v_mfma_f32_16x16x32_bf16 v[10:13], v[164:167], v[224:227], v[10:13]
	v_mfma_f32_16x16x32_bf16 v[62:65], v[150:153], v[196:199], v[62:65]
	v_mfma_f32_16x16x32_bf16 v[58:61], v[168:171], v[196:199], v[58:61]
	v_mfma_f32_16x16x32_bf16 v[46:49], v[150:153], v[204:207], v[46:49]
	v_mfma_f32_16x16x32_bf16 v[42:45], v[168:171], v[204:207], v[42:45]
	v_mfma_f32_16x16x32_bf16 v[30:33], v[150:153], v[218:221], v[30:33]
	v_mfma_f32_16x16x32_bf16 v[26:29], v[168:171], v[218:221], v[26:29]
	v_mfma_f32_16x16x32_bf16 v[14:17], v[150:153], v[228:231], v[14:17]
	v_mfma_f32_16x16x32_bf16 v[10:13], v[168:171], v[228:231], v[10:13]
	v_mfma_f32_16x16x32_bf16 v[54:57], v[172:175], v[192:195], v[54:57]
	v_mfma_f32_16x16x32_bf16 v[50:53], v[180:183], v[192:195], v[50:53]
	v_mfma_f32_16x16x32_bf16 v[38:41], v[172:175], v[200:203], v[38:41]
	v_mfma_f32_16x16x32_bf16 v[34:37], v[180:183], v[200:203], v[34:37]
	v_mfma_f32_16x16x32_bf16 v[22:25], v[172:175], v[208:211], v[22:25]
	v_mfma_f32_16x16x32_bf16 v[18:21], v[180:183], v[208:211], v[18:21]
	v_mfma_f32_16x16x32_bf16 v[6:9], v[172:175], v[224:227], v[6:9]
	v_mfma_f32_16x16x32_bf16 v[2:5], v[180:183], v[224:227], v[2:5]
	v_mfma_f32_16x16x32_bf16 v[54:57], v[176:179], v[196:199], v[54:57]
	v_mfma_f32_16x16x32_bf16 v[50:53], v[184:187], v[196:199], v[50:53]
	v_mfma_f32_16x16x32_bf16 v[38:41], v[176:179], v[204:207], v[38:41]
	v_mfma_f32_16x16x32_bf16 v[34:37], v[184:187], v[204:207], v[34:37]
	v_mfma_f32_16x16x32_bf16 v[22:25], v[176:179], v[218:221], v[22:25]
	v_mfma_f32_16x16x32_bf16 v[18:21], v[184:187], v[218:221], v[18:21]
	v_mfma_f32_16x16x32_bf16 v[6:9], v[176:179], v[228:231], v[6:9]
	v_mfma_f32_16x16x32_bf16 v[2:5], v[184:187], v[228:231], v[2:5]
	s_setprio 0
	s_barrier
	s_add_i32 s74, 0, 0x18000
	v_add_u32_e32 v161, s74, v155
	s_add_i32 s75, 0, 0x1c000
	ds_read_b128 v[146:149], v161
	ds_read_b128 v[150:153], v161 offset:1024
	ds_read_b128 v[164:167], v161 offset:2048
	ds_read_b128 v[168:171], v161 offset:3072
	v_add_u32_e32 v161, s75, v155
	ds_read_b128 v[172:175], v161
	ds_read_b128 v[176:179], v161 offset:1024
	ds_read_b128 v[180:183], v161 offset:2048
	ds_read_b128 v[184:187], v161 offset:3072
	s_add_u32 s72, s84, 0x40000
	s_addc_u32 s73, s85, 0
	s_mov_b32 m0, s95
	v_lshl_add_u64 v[236:237], s[72:73], 0, v[130:131]
	ds_read_b128 v[192:195], v159 offset:32768
	ds_read_b128 v[196:199], v159 offset:33792
	ds_read_b128 v[200:203], v159 offset:34816
	ds_read_b128 v[204:207], v159 offset:35840
	ds_read_b128 v[208:211], v159 offset:36864
	ds_read_b128 v[218:221], v159 offset:37888
	ds_read_b128 v[224:227], v159 offset:38912
	ds_read_b128 v[228:231], v159 offset:39936
	global_load_lds_dwordx4 v[236:237], off
	v_lshl_add_u64 v[236:237], s[72:73], 0, v[134:135]
	s_mov_b32 m0, s96
	s_nop 0
	global_load_lds_dwordx4 v[236:237], off
	s_waitcnt vmcnt(8)
	s_waitcnt lgkmcnt(0)
	s_barrier
	s_setprio 1
	s_waitcnt lgkmcnt(0)
	v_mfma_f32_16x16x32_bf16 v[126:129], v[146:149], v[192:195], v[126:129]
	v_mfma_f32_16x16x32_bf16 v[122:125], v[164:167], v[192:195], v[122:125]
	v_mfma_f32_16x16x32_bf16 v[110:113], v[146:149], v[200:203], v[110:113]
	v_mfma_f32_16x16x32_bf16 v[106:109], v[164:167], v[200:203], v[106:109]
	v_mfma_f32_16x16x32_bf16 v[94:97], v[146:149], v[208:211], v[94:97]
	v_mfma_f32_16x16x32_bf16 v[90:93], v[164:167], v[208:211], v[90:93]
	v_mfma_f32_16x16x32_bf16 v[78:81], v[146:149], v[224:227], v[78:81]
	v_mfma_f32_16x16x32_bf16 v[74:77], v[164:167], v[224:227], v[74:77]
	v_mfma_f32_16x16x32_bf16 v[126:129], v[150:153], v[196:199], v[126:129]
	v_mfma_f32_16x16x32_bf16 v[122:125], v[168:171], v[196:199], v[122:125]
	v_mfma_f32_16x16x32_bf16 v[110:113], v[150:153], v[204:207], v[110:113]
	v_mfma_f32_16x16x32_bf16 v[106:109], v[168:171], v[204:207], v[106:109]
	v_mfma_f32_16x16x32_bf16 v[94:97], v[150:153], v[218:221], v[94:97]
	v_mfma_f32_16x16x32_bf16 v[90:93], v[168:171], v[218:221], v[90:93]
	v_mfma_f32_16x16x32_bf16 v[78:81], v[150:153], v[228:231], v[78:81]
	v_mfma_f32_16x16x32_bf16 v[74:77], v[168:171], v[228:231], v[74:77]
	v_mfma_f32_16x16x32_bf16 v[118:121], v[172:175], v[192:195], v[118:121]
	v_mfma_f32_16x16x32_bf16 v[114:117], v[180:183], v[192:195], v[114:117]
	v_mfma_f32_16x16x32_bf16 v[102:105], v[172:175], v[200:203], v[102:105]
	v_mfma_f32_16x16x32_bf16 v[98:101], v[180:183], v[200:203], v[98:101]
	v_mfma_f32_16x16x32_bf16 v[86:89], v[172:175], v[208:211], v[86:89]
	v_mfma_f32_16x16x32_bf16 v[82:85], v[180:183], v[208:211], v[82:85]
	v_mfma_f32_16x16x32_bf16 v[70:73], v[172:175], v[224:227], v[70:73]
	v_mfma_f32_16x16x32_bf16 v[66:69], v[180:183], v[224:227], v[66:69]
	v_mfma_f32_16x16x32_bf16 v[118:121], v[176:179], v[196:199], v[118:121]
	v_mfma_f32_16x16x32_bf16 v[114:117], v[184:187], v[196:199], v[114:117]
	v_mfma_f32_16x16x32_bf16 v[102:105], v[176:179], v[204:207], v[102:105]
	v_mfma_f32_16x16x32_bf16 v[98:101], v[184:187], v[204:207], v[98:101]
	v_mfma_f32_16x16x32_bf16 v[86:89], v[176:179], v[218:221], v[86:89]
	v_mfma_f32_16x16x32_bf16 v[82:85], v[184:187], v[218:221], v[82:85]
	v_mfma_f32_16x16x32_bf16 v[70:73], v[176:179], v[228:231], v[70:73]
	v_mfma_f32_16x16x32_bf16 v[66:69], v[184:187], v[228:231], v[66:69]
	s_setprio 0
	s_barrier
	s_add_i32 s72, s74, s92
	v_lshl_add_u64 v[188:189], v[188:189], 0, s[36:37]
	s_mov_b32 m0, s72
	ds_read_b128 v[192:195], v159 offset:49152
	ds_read_b128 v[196:199], v159 offset:50176
	ds_read_b128 v[200:203], v159 offset:51200
	ds_read_b128 v[204:207], v159 offset:52224
	ds_read_b128 v[208:211], v159 offset:53248
	ds_read_b128 v[218:221], v159 offset:54272
	ds_read_b128 v[224:227], v159 offset:55296
	ds_read_b128 v[228:231], v159 offset:56320
	global_load_lds_dwordx4 v[188:189], off
	s_add_i32 m0, s72, 0x2000
	s_add_u32 s72, s78, 0x40080
	v_lshl_add_u64 v[188:189], v[214:215], 0, s[36:37]
	s_addc_u32 s73, s79, 0
	s_add_i32 s74, s75, s92
	global_load_lds_dwordx4 v[188:189], off
	v_lshl_add_u64 v[188:189], s[72:73], 0, v[132:133]
	s_mov_b32 m0, s74
	s_nop 0
	global_load_lds_dwordx4 v[188:189], off
	v_lshl_add_u64 v[188:189], s[72:73], 0, v[136:137]
	s_add_i32 m0, s74, 0x2000
	s_nop 0
	global_load_lds_dwordx4 v[188:189], off
	v_lshl_add_u64 v[188:189], v[232:233], 0, s[36:37]
	s_mov_b32 m0, s86
	s_nop 0
	global_load_lds_dwordx4 v[188:189], off
	v_lshl_add_u64 v[188:189], v[234:235], 0, s[36:37]
	s_mov_b32 m0, s87
	s_nop 0
	global_load_lds_dwordx4 v[188:189], off
	s_waitcnt vmcnt(8)
	s_waitcnt lgkmcnt(0)
	s_barrier
	s_setprio 1
	s_waitcnt lgkmcnt(0)
	v_mfma_f32_16x16x32_bf16 v[62:65], v[146:149], v[192:195], v[62:65]
	v_mfma_f32_16x16x32_bf16 v[58:61], v[164:167], v[192:195], v[58:61]
	v_mfma_f32_16x16x32_bf16 v[46:49], v[146:149], v[200:203], v[46:49]
	v_mfma_f32_16x16x32_bf16 v[42:45], v[164:167], v[200:203], v[42:45]
	v_mfma_f32_16x16x32_bf16 v[30:33], v[146:149], v[208:211], v[30:33]
	v_mfma_f32_16x16x32_bf16 v[26:29], v[164:167], v[208:211], v[26:29]
	v_mfma_f32_16x16x32_bf16 v[14:17], v[146:149], v[224:227], v[14:17]
	v_mfma_f32_16x16x32_bf16 v[10:13], v[164:167], v[224:227], v[10:13]
	v_mfma_f32_16x16x32_bf16 v[62:65], v[150:153], v[196:199], v[62:65]
	v_mfma_f32_16x16x32_bf16 v[58:61], v[168:171], v[196:199], v[58:61]
	v_mfma_f32_16x16x32_bf16 v[46:49], v[150:153], v[204:207], v[46:49]
	v_mfma_f32_16x16x32_bf16 v[42:45], v[168:171], v[204:207], v[42:45]
	v_mfma_f32_16x16x32_bf16 v[30:33], v[150:153], v[218:221], v[30:33]
	v_mfma_f32_16x16x32_bf16 v[26:29], v[168:171], v[218:221], v[26:29]
	v_mfma_f32_16x16x32_bf16 v[14:17], v[150:153], v[228:231], v[14:17]
	v_mfma_f32_16x16x32_bf16 v[10:13], v[168:171], v[228:231], v[10:13]
	v_mfma_f32_16x16x32_bf16 v[54:57], v[172:175], v[192:195], v[54:57]
	v_mfma_f32_16x16x32_bf16 v[50:53], v[180:183], v[192:195], v[50:53]
	v_mfma_f32_16x16x32_bf16 v[38:41], v[172:175], v[200:203], v[38:41]
	v_mfma_f32_16x16x32_bf16 v[34:37], v[180:183], v[200:203], v[34:37]
	v_mfma_f32_16x16x32_bf16 v[22:25], v[172:175], v[208:211], v[22:25]
	v_mfma_f32_16x16x32_bf16 v[18:21], v[180:183], v[208:211], v[18:21]
	v_mfma_f32_16x16x32_bf16 v[6:9], v[172:175], v[224:227], v[6:9]
	v_mfma_f32_16x16x32_bf16 v[2:5], v[180:183], v[224:227], v[2:5]
	v_mfma_f32_16x16x32_bf16 v[54:57], v[176:179], v[196:199], v[54:57]
	v_mfma_f32_16x16x32_bf16 v[50:53], v[184:187], v[196:199], v[50:53]
	v_mfma_f32_16x16x32_bf16 v[38:41], v[176:179], v[204:207], v[38:41]
	v_mfma_f32_16x16x32_bf16 v[34:37], v[184:187], v[204:207], v[34:37]
	v_mfma_f32_16x16x32_bf16 v[22:25], v[176:179], v[218:221], v[22:25]
	v_mfma_f32_16x16x32_bf16 v[18:21], v[184:187], v[218:221], v[18:21]
	v_mfma_f32_16x16x32_bf16 v[6:9], v[176:179], v[228:231], v[6:9]
	v_mfma_f32_16x16x32_bf16 v[2:5], v[184:187], v[228:231], v[2:5]
	s_setprio 0
	s_barrier
	s_add_i32 s71, s71, 2
	s_add_u32 s76, s76, 0x100
	s_addc_u32 s77, s77, 0
	s_add_u32 s69, s69, 0x100
	s_addc_u32 s70, s70, 0
	s_cmp_gt_u32 s71, 13
	s_cbranch_scc0 .LBB0_202
	s_and_b64 vcc, exec, s[38:39]
	s_cbranch_vccz .LBB0_205
	s_barrier

.LBB0_645:
	s_or_b64 exec, exec, s[34:35]
	s_waitcnt vmcnt(0)
	s_and_b64 s[36:37], s[4:5], s[6:7]
	s_and_saveexec_b64 s[34:35], s[36:37]
	s_cbranch_execz .LBB0_648
	s_mov_b64 s[36:37], exec
	v_mbcnt_lo_u32_b32 v16, s36, 0
	v_mbcnt_hi_u32_b32 v16, s37, v16
	v_cmp_eq_u32_e32 vcc, 0, v16
	s_and_b64 s[48:49], exec, vcc
	s_mov_b64 exec, s[48:49]
	s_cbranch_execz .LBB0_648
	s_bcnt1_i32_b64 s31, s[36:37]
	v_mov_b32_e32 v16, s31
	global_atomic_add v133, v16, s[20:21]

.LBB0_651:
	global_load_dword v17, v133, s[20:21] sc1
	v_subrev_co_u32_e32 v16, vcc, 1, v16
	s_waitcnt vmcnt(0)
	v_readfirstlane_b32 s31, v17
	s_cmpk_gt_u32 s31, 0x3f
	s_cselect_b64 s[36:37], -1, 0
	s_or_b64 s[36:37], s[36:37], vcc
	s_and_b64 vcc, exec, s[36:37]
	s_cbranch_vccz .LBB0_650

.LBB0_679:
	v_add_u32_e32 v168, s47, v153
	v_add_u32_e32 v184, s48, v153
	s_add_u32 s30, s16, s28
	ds_read_b128 v[156:159], v168
	ds_read_b128 v[160:163], v168 offset:1024
	ds_read_b128 v[164:167], v168 offset:2048
	ds_read_b128 v[168:171], v168 offset:3072
	ds_read_b128 v[172:175], v184
	ds_read_b128 v[176:179], v184 offset:1024
	ds_read_b128 v[180:183], v184 offset:2048
	ds_read_b128 v[184:187], v184 offset:3072
	s_addc_u32 s31, s17, s29
	s_add_u32 s30, s30, 0x100
	s_addc_u32 s31, s31, 0
	s_add_u32 s61, s50, s28
	s_addc_u32 s64, s51, s29
	s_cmpk_eq_i32 s28, 0x700
	s_cselect_b32 s35, s23, s31
	s_cselect_b32 s34, s58, s30
	s_cselect_b32 s31, s21, s64
	s_cselect_b32 s30, s59, s61
	v_lshl_add_u64 v[188:189], v[148:149], 0, s[28:29]
	s_add_i32 m0, s13, 0xc000
	ds_read_b128 v[192:195], v154
	ds_read_b128 v[196:199], v154 offset:1024
	ds_read_b128 v[200:203], v154 offset:2048
	ds_read_b128 v[204:207], v154 offset:3072
	ds_read_b128 v[208:211], v154 offset:4096
	ds_read_b128 v[218:221], v154 offset:5120
	ds_read_b128 v[226:229], v154 offset:6144
	ds_read_b128 v[230:233], v154 offset:7168
	global_load_lds_dwordx4 v[188:189], off
	v_lshl_add_u64 v[188:189], v[150:151], 0, s[28:29]
	s_add_i32 m0, s13, 0xe000
	s_nop 0
	global_load_lds_dwordx4 v[188:189], off
	s_waitcnt vmcnt(8)
	s_waitcnt lgkmcnt(0)
	s_barrier
	s_setprio 1
	s_waitcnt lgkmcnt(0)
	v_mfma_f32_16x16x32_bf16 v[128:131], v[156:159], v[192:195], v[128:131]
	v_mfma_f32_16x16x32_bf16 v[124:127], v[164:167], v[192:195], v[124:127]
	v_mfma_f32_16x16x32_bf16 v[112:115], v[156:159], v[200:203], v[112:115]
	v_mfma_f32_16x16x32_bf16 v[108:111], v[164:167], v[200:203], v[108:111]
	v_mfma_f32_16x16x32_bf16 v[96:99], v[156:159], v[208:211], v[96:99]
	v_mfma_f32_16x16x32_bf16 v[92:95], v[164:167], v[208:211], v[92:95]
	v_mfma_f32_16x16x32_bf16 v[80:83], v[156:159], v[226:229], v[80:83]
	v_mfma_f32_16x16x32_bf16 v[76:79], v[164:167], v[226:229], v[76:79]
	v_mfma_f32_16x16x32_bf16 v[128:131], v[160:163], v[196:199], v[128:131]
	v_mfma_f32_16x16x32_bf16 v[124:127], v[168:171], v[196:199], v[124:127]
	v_mfma_f32_16x16x32_bf16 v[112:115], v[160:163], v[204:207], v[112:115]
	v_mfma_f32_16x16x32_bf16 v[108:111], v[168:171], v[204:207], v[108:111]
	v_mfma_f32_16x16x32_bf16 v[96:99], v[160:163], v[218:221], v[96:99]
	v_mfma_f32_16x16x32_bf16 v[92:95], v[168:171], v[218:221], v[92:95]
	v_mfma_f32_16x16x32_bf16 v[80:83], v[160:163], v[230:233], v[80:83]
	v_mfma_f32_16x16x32_bf16 v[76:79], v[168:171], v[230:233], v[76:79]
	v_mfma_f32_16x16x32_bf16 v[120:123], v[172:175], v[192:195], v[120:123]
	v_mfma_f32_16x16x32_bf16 v[116:119], v[180:183], v[192:195], v[116:119]
	v_mfma_f32_16x16x32_bf16 v[104:107], v[172:175], v[200:203], v[104:107]
	v_mfma_f32_16x16x32_bf16 v[100:103], v[180:183], v[200:203], v[100:103]
	v_mfma_f32_16x16x32_bf16 v[88:91], v[172:175], v[208:211], v[88:91]
	v_mfma_f32_16x16x32_bf16 v[84:87], v[180:183], v[208:211], v[84:87]
	v_mfma_f32_16x16x32_bf16 v[72:75], v[172:175], v[226:229], v[72:75]
	v_mfma_f32_16x16x32_bf16 v[68:71], v[180:183], v[226:229], v[68:71]
	v_mfma_f32_16x16x32_bf16 v[120:123], v[176:179], v[196:199], v[120:123]
	v_mfma_f32_16x16x32_bf16 v[116:119], v[184:187], v[196:199], v[116:119]
	v_mfma_f32_16x16x32_bf16 v[104:107], v[176:179], v[204:207], v[104:107]
	v_mfma_f32_16x16x32_bf16 v[100:103], v[184:187], v[204:207], v[100:103]
	v_mfma_f32_16x16x32_bf16 v[88:91], v[176:179], v[218:221], v[88:91]
	v_mfma_f32_16x16x32_bf16 v[84:87], v[184:187], v[218:221], v[84:87]
	v_mfma_f32_16x16x32_bf16 v[72:75], v[176:179], v[230:233], v[72:75]
	v_mfma_f32_16x16x32_bf16 v[68:71], v[184:187], v[230:233], v[68:71]
	s_setprio 0
	s_barrier
	s_add_i32 s61, s47, s40
	v_lshl_add_u64 v[188:189], s[30:31], 0, v[134:135]
	s_mov_b32 m0, s61
	ds_read_b128 v[192:195], v154 offset:16384
	ds_read_b128 v[196:199], v154 offset:17408
	ds_read_b128 v[200:203], v154 offset:18432
	ds_read_b128 v[204:207], v154 offset:19456
	ds_read_b128 v[208:211], v154 offset:20480
	ds_read_b128 v[218:221], v154 offset:21504
	ds_read_b128 v[226:229], v154 offset:22528
	ds_read_b128 v[230:233], v154 offset:23552
	global_load_lds_dwordx4 v[188:189], off
	s_add_i32 m0, s61, 0x2000
	s_add_u32 s64, s30, 0x40000
	v_lshl_add_u64 v[234:235], s[30:31], 0, v[138:139]
	s_addc_u32 s65, s31, 0
	s_add_i32 s61, s48, s40
	global_load_lds_dwordx4 v[234:235], off
	v_lshl_add_u64 v[236:237], s[64:65], 0, v[134:135]
	s_mov_b32 m0, s61
	v_lshl_add_u64 v[238:239], s[34:35], 0, v[136:137]
	global_load_lds_dwordx4 v[236:237], off
	v_lshl_add_u64 v[236:237], s[64:65], 0, v[138:139]
	s_add_i32 m0, s61, 0x2000
	s_nop 0
	global_load_lds_dwordx4 v[236:237], off
	v_lshl_add_u64 v[236:237], s[34:35], 0, v[132:133]
	s_mov_b32 m0, s13
	s_nop 0
	global_load_lds_dwordx4 v[236:237], off
	s_mov_b32 m0, s41
	s_nop 0
	global_load_lds_dwordx4 v[238:239], off
	s_waitcnt vmcnt(8)
	s_waitcnt lgkmcnt(0)
	s_barrier
	s_setprio 1
	s_waitcnt lgkmcnt(0)
	v_mfma_f32_16x16x32_bf16 v[64:67], v[156:159], v[192:195], v[64:67]
	v_mfma_f32_16x16x32_bf16 v[60:63], v[164:167], v[192:195], v[60:63]
	v_mfma_f32_16x16x32_bf16 v[48:51], v[156:159], v[200:203], v[48:51]
	v_mfma_f32_16x16x32_bf16 v[44:47], v[164:167], v[200:203], v[44:47]
	v_mfma_f32_16x16x32_bf16 v[32:35], v[156:159], v[208:211], v[32:35]
	v_mfma_f32_16x16x32_bf16 v[28:31], v[164:167], v[208:211], v[28:31]
	v_mfma_f32_16x16x32_bf16 v[16:19], v[156:159], v[226:229], v[16:19]
	v_mfma_f32_16x16x32_bf16 v[12:15], v[164:167], v[226:229], v[12:15]
	v_mfma_f32_16x16x32_bf16 v[64:67], v[160:163], v[196:199], v[64:67]
	v_mfma_f32_16x16x32_bf16 v[60:63], v[168:171], v[196:199], v[60:63]
	v_mfma_f32_16x16x32_bf16 v[48:51], v[160:163], v[204:207], v[48:51]
	v_mfma_f32_16x16x32_bf16 v[44:47], v[168:171], v[204:207], v[44:47]
	v_mfma_f32_16x16x32_bf16 v[32:35], v[160:163], v[218:221], v[32:35]
	v_mfma_f32_16x16x32_bf16 v[28:31], v[168:171], v[218:221], v[28:31]
	v_mfma_f32_16x16x32_bf16 v[16:19], v[160:163], v[230:233], v[16:19]
	v_mfma_f32_16x16x32_bf16 v[12:15], v[168:171], v[230:233], v[12:15]
	v_mfma_f32_16x16x32_bf16 v[56:59], v[172:175], v[192:195], v[56:59]
	v_mfma_f32_16x16x32_bf16 v[52:55], v[180:183], v[192:195], v[52:55]
	v_mfma_f32_16x16x32_bf16 v[40:43], v[172:175], v[200:203], v[40:43]
	v_mfma_f32_16x16x32_bf16 v[36:39], v[180:183], v[200:203], v[36:39]
	v_mfma_f32_16x16x32_bf16 v[24:27], v[172:175], v[208:211], v[24:27]
	v_mfma_f32_16x16x32_bf16 v[20:23], v[180:183], v[208:211], v[20:23]
	v_mfma_f32_16x16x32_bf16 v[8:11], v[172:175], v[226:229], v[8:11]
	v_mfma_f32_16x16x32_bf16 v[4:7], v[180:183], v[226:229], v[4:7]
	v_mfma_f32_16x16x32_bf16 v[56:59], v[176:179], v[196:199], v[56:59]
	v_mfma_f32_16x16x32_bf16 v[52:55], v[184:187], v[196:199], v[52:55]
	v_mfma_f32_16x16x32_bf16 v[40:43], v[176:179], v[204:207], v[40:43]
	v_mfma_f32_16x16x32_bf16 v[36:39], v[184:187], v[204:207], v[36:39]
	v_mfma_f32_16x16x32_bf16 v[24:27], v[176:179], v[218:221], v[24:27]
	v_mfma_f32_16x16x32_bf16 v[20:23], v[184:187], v[218:221], v[20:23]
	v_mfma_f32_16x16x32_bf16 v[8:11], v[176:179], v[230:233], v[8:11]
	v_mfma_f32_16x16x32_bf16 v[4:7], v[184:187], v[230:233], v[4:7]
	s_setprio 0
	s_barrier
	s_add_i32 s61, 0, 0x18000
	s_add_i32 s64, 0, 0x1c000
	v_add_u32_e32 v168, s61, v153
	v_add_u32_e32 v184, s64, v153
	ds_read_b128 v[156:159], v168
	ds_read_b128 v[160:163], v168 offset:1024
	ds_read_b128 v[164:167], v168 offset:2048
	ds_read_b128 v[168:171], v168 offset:3072
	ds_read_b128 v[172:175], v184
	ds_read_b128 v[176:179], v184 offset:1024
	ds_read_b128 v[180:183], v184 offset:2048
	ds_read_b128 v[184:187], v184 offset:3072
	s_add_u32 s34, s34, 0x40000
	s_addc_u32 s35, s35, 0
	s_mov_b32 m0, s42
	v_lshl_add_u64 v[240:241], s[34:35], 0, v[132:133]
	ds_read_b128 v[192:195], v154 offset:32768
	ds_read_b128 v[196:199], v154 offset:33792
	ds_read_b128 v[200:203], v154 offset:34816
	ds_read_b128 v[204:207], v154 offset:35840
	ds_read_b128 v[208:211], v154 offset:36864
	ds_read_b128 v[218:221], v154 offset:37888
	ds_read_b128 v[226:229], v154 offset:38912
	ds_read_b128 v[230:233], v154 offset:39936
	global_load_lds_dwordx4 v[240:241], off
	v_lshl_add_u64 v[240:241], s[34:35], 0, v[136:137]
	s_mov_b32 m0, s43
	s_nop 0
	global_load_lds_dwordx4 v[240:241], off
	s_waitcnt vmcnt(8)
	s_waitcnt lgkmcnt(0)
	s_barrier
	s_setprio 1
	s_waitcnt lgkmcnt(0)
	v_mfma_f32_16x16x32_bf16 v[128:131], v[156:159], v[192:195], v[128:131]
	v_mfma_f32_16x16x32_bf16 v[124:127], v[164:167], v[192:195], v[124:127]
	v_mfma_f32_16x16x32_bf16 v[112:115], v[156:159], v[200:203], v[112:115]
	v_mfma_f32_16x16x32_bf16 v[108:111], v[164:167], v[200:203], v[108:111]
	v_mfma_f32_16x16x32_bf16 v[96:99], v[156:159], v[208:211], v[96:99]
	v_mfma_f32_16x16x32_bf16 v[92:95], v[164:167], v[208:211], v[92:95]
	v_mfma_f32_16x16x32_bf16 v[80:83], v[156:159], v[226:229], v[80:83]
	v_mfma_f32_16x16x32_bf16 v[76:79], v[164:167], v[226:229], v[76:79]
	v_mfma_f32_16x16x32_bf16 v[128:131], v[160:163], v[196:199], v[128:131]
	v_mfma_f32_16x16x32_bf16 v[124:127], v[168:171], v[196:199], v[124:127]
	v_mfma_f32_16x16x32_bf16 v[112:115], v[160:163], v[204:207], v[112:115]
	v_mfma_f32_16x16x32_bf16 v[108:111], v[168:171], v[204:207], v[108:111]
	v_mfma_f32_16x16x32_bf16 v[96:99], v[160:163], v[218:221], v[96:99]
	v_mfma_f32_16x16x32_bf16 v[92:95], v[168:171], v[218:221], v[92:95]
	v_mfma_f32_16x16x32_bf16 v[80:83], v[160:163], v[230:233], v[80:83]
	v_mfma_f32_16x16x32_bf16 v[76:79], v[168:171], v[230:233], v[76:79]
	v_mfma_f32_16x16x32_bf16 v[120:123], v[172:175], v[192:195], v[120:123]
	v_mfma_f32_16x16x32_bf16 v[116:119], v[180:183], v[192:195], v[116:119]
	v_mfma_f32_16x16x32_bf16 v[104:107], v[172:175], v[200:203], v[104:107]
	v_mfma_f32_16x16x32_bf16 v[100:103], v[180:183], v[200:203], v[100:103]
	v_mfma_f32_16x16x32_bf16 v[88:91], v[172:175], v[208:211], v[88:91]
	v_mfma_f32_16x16x32_bf16 v[84:87], v[180:183], v[208:211], v[84:87]
	v_mfma_f32_16x16x32_bf16 v[72:75], v[172:175], v[226:229], v[72:75]
	v_mfma_f32_16x16x32_bf16 v[68:71], v[180:183], v[226:229], v[68:71]
	v_mfma_f32_16x16x32_bf16 v[120:123], v[176:179], v[196:199], v[120:123]
	v_mfma_f32_16x16x32_bf16 v[116:119], v[184:187], v[196:199], v[116:119]
	v_mfma_f32_16x16x32_bf16 v[104:107], v[176:179], v[204:207], v[104:107]
	v_mfma_f32_16x16x32_bf16 v[100:103], v[184:187], v[204:207], v[100:103]
	v_mfma_f32_16x16x32_bf16 v[88:91], v[176:179], v[218:221], v[88:91]
	v_mfma_f32_16x16x32_bf16 v[84:87], v[184:187], v[218:221], v[84:87]
	v_mfma_f32_16x16x32_bf16 v[72:75], v[176:179], v[230:233], v[72:75]
	v_mfma_f32_16x16x32_bf16 v[68:71], v[184:187], v[230:233], v[68:71]
	s_setprio 0
	s_barrier
	s_add_i32 s34, s61, s40
	v_lshl_add_u64 v[188:189], v[188:189], 0, s[18:19]
	s_mov_b32 m0, s34
	ds_read_b128 v[192:195], v154 offset:49152
	ds_read_b128 v[196:199], v154 offset:50176
	ds_read_b128 v[200:203], v154 offset:51200
	ds_read_b128 v[204:207], v154 offset:52224
	ds_read_b128 v[208:211], v154 offset:53248
	ds_read_b128 v[218:221], v154 offset:54272
	ds_read_b128 v[226:229], v154 offset:55296
	ds_read_b128 v[230:233], v154 offset:56320
	global_load_lds_dwordx4 v[188:189], off
	s_add_i32 m0, s34, 0x2000
	s_add_u32 s30, s30, 0x40080
	v_lshl_add_u64 v[188:189], v[234:235], 0, s[18:19]
	s_addc_u32 s31, s31, 0
	s_add_i32 s34, s64, s40
	global_load_lds_dwordx4 v[188:189], off
	v_lshl_add_u64 v[188:189], s[30:31], 0, v[134:135]
	s_mov_b32 m0, s34
	s_nop 0
	global_load_lds_dwordx4 v[188:189], off
	v_lshl_add_u64 v[188:189], s[30:31], 0, v[138:139]
	s_add_i32 m0, s34, 0x2000
	s_nop 0
	global_load_lds_dwordx4 v[188:189], off
	v_lshl_add_u64 v[188:189], v[236:237], 0, s[18:19]
	s_mov_b32 m0, s44
	s_nop 0
	global_load_lds_dwordx4 v[188:189], off
	v_lshl_add_u64 v[188:189], v[238:239], 0, s[18:19]
	s_mov_b32 m0, s45
	s_nop 0
	global_load_lds_dwordx4 v[188:189], off
	s_waitcnt vmcnt(8)
	s_waitcnt lgkmcnt(0)
	s_barrier
	s_setprio 1
	s_waitcnt lgkmcnt(0)
	v_mfma_f32_16x16x32_bf16 v[64:67], v[156:159], v[192:195], v[64:67]
	v_mfma_f32_16x16x32_bf16 v[60:63], v[164:167], v[192:195], v[60:63]
	v_mfma_f32_16x16x32_bf16 v[48:51], v[156:159], v[200:203], v[48:51]
	v_mfma_f32_16x16x32_bf16 v[44:47], v[164:167], v[200:203], v[44:47]
	v_mfma_f32_16x16x32_bf16 v[32:35], v[156:159], v[208:211], v[32:35]
	v_mfma_f32_16x16x32_bf16 v[28:31], v[164:167], v[208:211], v[28:31]
	v_mfma_f32_16x16x32_bf16 v[16:19], v[156:159], v[226:229], v[16:19]
	v_mfma_f32_16x16x32_bf16 v[12:15], v[164:167], v[226:229], v[12:15]
	v_mfma_f32_16x16x32_bf16 v[64:67], v[160:163], v[196:199], v[64:67]
	v_mfma_f32_16x16x32_bf16 v[60:63], v[168:171], v[196:199], v[60:63]
	v_mfma_f32_16x16x32_bf16 v[48:51], v[160:163], v[204:207], v[48:51]
	v_mfma_f32_16x16x32_bf16 v[44:47], v[168:171], v[204:207], v[44:47]
	v_mfma_f32_16x16x32_bf16 v[32:35], v[160:163], v[218:221], v[32:35]
	v_mfma_f32_16x16x32_bf16 v[28:31], v[168:171], v[218:221], v[28:31]
	v_mfma_f32_16x16x32_bf16 v[16:19], v[160:163], v[230:233], v[16:19]
	v_mfma_f32_16x16x32_bf16 v[12:15], v[168:171], v[230:233], v[12:15]
	v_mfma_f32_16x16x32_bf16 v[56:59], v[172:175], v[192:195], v[56:59]
	v_mfma_f32_16x16x32_bf16 v[52:55], v[180:183], v[192:195], v[52:55]
	v_mfma_f32_16x16x32_bf16 v[40:43], v[172:175], v[200:203], v[40:43]
	v_mfma_f32_16x16x32_bf16 v[36:39], v[180:183], v[200:203], v[36:39]
	v_mfma_f32_16x16x32_bf16 v[24:27], v[172:175], v[208:211], v[24:27]
	v_mfma_f32_16x16x32_bf16 v[20:23], v[180:183], v[208:211], v[20:23]
	v_mfma_f32_16x16x32_bf16 v[8:11], v[172:175], v[226:229], v[8:11]
	v_mfma_f32_16x16x32_bf16 v[4:7], v[180:183], v[226:229], v[4:7]
	v_mfma_f32_16x16x32_bf16 v[56:59], v[176:179], v[196:199], v[56:59]
	v_mfma_f32_16x16x32_bf16 v[52:55], v[184:187], v[196:199], v[52:55]
	v_mfma_f32_16x16x32_bf16 v[40:43], v[176:179], v[204:207], v[40:43]
	v_mfma_f32_16x16x32_bf16 v[36:39], v[184:187], v[204:207], v[36:39]
	v_mfma_f32_16x16x32_bf16 v[24:27], v[176:179], v[218:221], v[24:27]
	v_mfma_f32_16x16x32_bf16 v[20:23], v[184:187], v[218:221], v[20:23]
	v_mfma_f32_16x16x32_bf16 v[8:11], v[176:179], v[230:233], v[8:11]
	v_mfma_f32_16x16x32_bf16 v[4:7], v[184:187], v[230:233], v[4:7]
	s_setprio 0
	s_barrier
	s_add_i32 s60, s60, 2
	s_add_u32 s28, s28, 0x100
	s_addc_u32 s29, s29, 0
	s_cmp_gt_u32 s60, 13
	s_cbranch_scc0 .LBB0_679
	s_add_u32 s28, s50, 0xffffff00
	s_addc_u32 s29, s51, -1
	s_andn2_b64 vcc, exec, s[4:5]
	s_cbranch_vccnz .LBB0_670
	v_mov_b32_e32 v4, 0
	s_mov_b32 s6, s20
	s_mov_b32 s12, s22
	s_mov_b64 s[16:17], s[26:27]
	s_mov_b32 s46, s49
	v_mov_b32_e32 v5, v4
	v_mov_b32_e32 v6, v4
	v_mov_b32_e32 v7, v4
	v_mov_b32_e32 v8, v4
	v_mov_b32_e32 v9, v4
	v_mov_b32_e32 v10, v4
	v_mov_b32_e32 v11, v4
	v_mov_b32_e32 v20, v4
	v_mov_b32_e32 v21, v4
	v_mov_b32_e32 v22, v4
	v_mov_b32_e32 v23, v4
	v_mov_b32_e32 v24, v4
	v_mov_b32_e32 v25, v4
	v_mov_b32_e32 v26, v4
	v_mov_b32_e32 v27, v4
	v_mov_b32_e32 v36, v4
	v_mov_b32_e32 v37, v4
	v_mov_b32_e32 v38, v4
	v_mov_b32_e32 v39, v4
	v_mov_b32_e32 v40, v4
	v_mov_b32_e32 v41, v4
	v_mov_b32_e32 v42, v4
	v_mov_b32_e32 v43, v4
	v_mov_b32_e32 v52, v4
	v_mov_b32_e32 v53, v4
	v_mov_b32_e32 v54, v4
	v_mov_b32_e32 v55, v4
	v_mov_b32_e32 v56, v4
	v_mov_b32_e32 v57, v4
	v_mov_b32_e32 v58, v4
	v_mov_b32_e32 v59, v4
	v_mov_b32_e32 v12, v4
	v_mov_b32_e32 v13, v4
	v_mov_b32_e32 v14, v4
	v_mov_b32_e32 v15, v4
	v_mov_b32_e32 v16, v4
	v_mov_b32_e32 v17, v4
	v_mov_b32_e32 v18, v4
	v_mov_b32_e32 v19, v4
	v_mov_b32_e32 v28, v4
	v_mov_b32_e32 v29, v4
	v_mov_b32_e32 v30, v4
	v_mov_b32_e32 v31, v4
	v_mov_b32_e32 v32, v4
	v_mov_b32_e32 v33, v4
	v_mov_b32_e32 v34, v4
	v_mov_b32_e32 v35, v4
	v_mov_b32_e32 v44, v4
	v_mov_b32_e32 v45, v4
	v_mov_b32_e32 v46, v4
	v_mov_b32_e32 v47, v4
	v_mov_b32_e32 v48, v4
	v_mov_b32_e32 v49, v4
	v_mov_b32_e32 v50, v4
	v_mov_b32_e32 v51, v4
	v_mov_b32_e32 v60, v4
	v_mov_b32_e32 v61, v4
	v_mov_b32_e32 v62, v4
	v_mov_b32_e32 v63, v4
	v_mov_b32_e32 v64, v4
	v_mov_b32_e32 v65, v4
	v_mov_b32_e32 v66, v4
	v_mov_b32_e32 v67, v4
	v_mov_b32_e32 v68, v4
	v_mov_b32_e32 v69, v4
	v_mov_b32_e32 v70, v4
	v_mov_b32_e32 v71, v4
	v_mov_b32_e32 v72, v4
	v_mov_b32_e32 v73, v4
	v_mov_b32_e32 v74, v4
	v_mov_b32_e32 v75, v4
	v_mov_b32_e32 v84, v4
	v_mov_b32_e32 v85, v4
	v_mov_b32_e32 v86, v4
	v_mov_b32_e32 v87, v4
	v_mov_b32_e32 v88, v4
	v_mov_b32_e32 v89, v4
	v_mov_b32_e32 v90, v4
	v_mov_b32_e32 v91, v4
	v_mov_b32_e32 v100, v4
	v_mov_b32_e32 v101, v4
	v_mov_b32_e32 v102, v4
	v_mov_b32_e32 v103, v4
	v_mov_b32_e32 v104, v4
	v_mov_b32_e32 v105, v4
	v_mov_b32_e32 v106, v4
	v_mov_b32_e32 v107, v4
	v_mov_b32_e32 v116, v4
	v_mov_b32_e32 v117, v4
	v_mov_b32_e32 v118, v4
	v_mov_b32_e32 v119, v4
	v_mov_b32_e32 v120, v4
	v_mov_b32_e32 v121, v4
	v_mov_b32_e32 v122, v4
	v_mov_b32_e32 v123, v4
	v_mov_b32_e32 v76, v4
	v_mov_b32_e32 v77, v4
	v_mov_b32_e32 v78, v4
	v_mov_b32_e32 v79, v4
	v_mov_b32_e32 v80, v4
	v_mov_b32_e32 v81, v4
	v_mov_b32_e32 v82, v4
	v_mov_b32_e32 v83, v4
	v_mov_b32_e32 v92, v4
	v_mov_b32_e32 v93, v4
	v_mov_b32_e32 v94, v4
	v_mov_b32_e32 v95, v4
	v_mov_b32_e32 v96, v4
	v_mov_b32_e32 v97, v4
	v_mov_b32_e32 v98, v4
	v_mov_b32_e32 v99, v4
	v_mov_b32_e32 v108, v4
	v_mov_b32_e32 v109, v4
	v_mov_b32_e32 v110, v4
	v_mov_b32_e32 v111, v4
	v_mov_b32_e32 v112, v4
	v_mov_b32_e32 v113, v4
	v_mov_b32_e32 v114, v4
	v_mov_b32_e32 v115, v4
	v_mov_b32_e32 v124, v4
	v_mov_b32_e32 v125, v4
	v_mov_b32_e32 v126, v4
	v_mov_b32_e32 v127, v4
	v_mov_b32_e32 v128, v4
	v_mov_b32_e32 v129, v4
	v_mov_b32_e32 v130, v4
	v_mov_b32_e32 v131, v4
	s_andn2_b64 vcc, exec, s[0:1]
	s_cbranch_vccnz .LBB0_671

.LBB0_820:
	ds_read_b128 v[148:151], v158
	ds_read_b128 v[162:165], v158 offset:1024
	ds_read_b128 v[166:169], v158 offset:2048
	ds_read_b128 v[170:173], v158 offset:3072
	ds_read_b128 v[174:177], v159
	ds_read_b128 v[178:181], v159 offset:1024
	ds_read_b128 v[182:185], v159 offset:2048
	ds_read_b128 v[186:189], v159 offset:3072
	s_add_u32 s40, s38, 0xfffc0080
	s_addc_u32 s41, s39, -1
	s_cmp_eq_u32 s71, 12
	s_cselect_b32 s43, s29, s41
	s_cselect_b32 s42, s67, s40
	s_cselect_b32 s41, s27, s70
	s_cselect_b32 s40, s68, s69
	v_lshl_add_u64 v[152:153], s[38:39], 0, v[140:141]
	s_add_i32 m0, s37, 0xc000
	ds_read_b128 v[190:193], v160
	ds_read_b128 v[194:197], v160 offset:1024
	ds_read_b128 v[198:201], v160 offset:2048
	ds_read_b128 v[202:205], v160 offset:3072
	ds_read_b128 v[206:209], v160 offset:4096
	ds_read_b128 v[218:221], v160 offset:5120
	ds_read_b128 v[226:229], v160 offset:6144
	ds_read_b128 v[230:233], v160 offset:7168
	global_load_lds_dwordx4 v[152:153], off
	v_lshl_add_u64 v[152:153], s[38:39], 0, v[142:143]
	s_add_i32 m0, s37, 0xe000
	s_nop 0
	global_load_lds_dwordx4 v[152:153], off
	s_waitcnt vmcnt(8)
	s_waitcnt lgkmcnt(0)
	s_barrier
	s_setprio 1
	s_waitcnt lgkmcnt(0)
	v_mfma_f32_16x16x32_bf16 v[128:131], v[148:151], v[190:193], v[128:131]
	v_mfma_f32_16x16x32_bf16 v[124:127], v[166:169], v[190:193], v[124:127]
	v_mfma_f32_16x16x32_bf16 v[112:115], v[148:151], v[198:201], v[112:115]
	v_mfma_f32_16x16x32_bf16 v[108:111], v[166:169], v[198:201], v[108:111]
	v_mfma_f32_16x16x32_bf16 v[96:99], v[148:151], v[206:209], v[96:99]
	v_mfma_f32_16x16x32_bf16 v[92:95], v[166:169], v[206:209], v[92:95]
	v_mfma_f32_16x16x32_bf16 v[80:83], v[148:151], v[226:229], v[80:83]
	v_mfma_f32_16x16x32_bf16 v[76:79], v[166:169], v[226:229], v[76:79]
	v_mfma_f32_16x16x32_bf16 v[128:131], v[162:165], v[194:197], v[128:131]
	v_mfma_f32_16x16x32_bf16 v[124:127], v[170:173], v[194:197], v[124:127]
	v_mfma_f32_16x16x32_bf16 v[112:115], v[162:165], v[202:205], v[112:115]
	v_mfma_f32_16x16x32_bf16 v[108:111], v[170:173], v[202:205], v[108:111]
	v_mfma_f32_16x16x32_bf16 v[96:99], v[162:165], v[218:221], v[96:99]
	v_mfma_f32_16x16x32_bf16 v[92:95], v[170:173], v[218:221], v[92:95]
	v_mfma_f32_16x16x32_bf16 v[80:83], v[162:165], v[230:233], v[80:83]
	v_mfma_f32_16x16x32_bf16 v[76:79], v[170:173], v[230:233], v[76:79]
	v_mfma_f32_16x16x32_bf16 v[120:123], v[174:177], v[190:193], v[120:123]
	v_mfma_f32_16x16x32_bf16 v[116:119], v[182:185], v[190:193], v[116:119]
	v_mfma_f32_16x16x32_bf16 v[104:107], v[174:177], v[198:201], v[104:107]
	v_mfma_f32_16x16x32_bf16 v[100:103], v[182:185], v[198:201], v[100:103]
	v_mfma_f32_16x16x32_bf16 v[88:91], v[174:177], v[206:209], v[88:91]
	v_mfma_f32_16x16x32_bf16 v[84:87], v[182:185], v[206:209], v[84:87]
	v_mfma_f32_16x16x32_bf16 v[72:75], v[174:177], v[226:229], v[72:75]
	v_mfma_f32_16x16x32_bf16 v[68:71], v[182:185], v[226:229], v[68:71]
	v_mfma_f32_16x16x32_bf16 v[120:123], v[178:181], v[194:197], v[120:123]
	v_mfma_f32_16x16x32_bf16 v[116:119], v[186:189], v[194:197], v[116:119]
	v_mfma_f32_16x16x32_bf16 v[104:107], v[178:181], v[202:205], v[104:107]
	v_mfma_f32_16x16x32_bf16 v[100:103], v[186:189], v[202:205], v[100:103]
	v_mfma_f32_16x16x32_bf16 v[88:91], v[178:181], v[218:221], v[88:91]
	v_mfma_f32_16x16x32_bf16 v[84:87], v[186:189], v[218:221], v[84:87]
	v_mfma_f32_16x16x32_bf16 v[72:75], v[178:181], v[230:233], v[72:75]
	v_mfma_f32_16x16x32_bf16 v[68:71], v[186:189], v[230:233], v[68:71]
	s_setprio 0
	s_barrier
	s_add_i32 s72, s58, s33
	v_lshl_add_u64 v[152:153], s[40:41], 0, v[134:135]
	s_mov_b32 m0, s72
	ds_read_b128 v[190:193], v160 offset:16384
	ds_read_b128 v[194:197], v160 offset:17408
	ds_read_b128 v[198:201], v160 offset:18432
	ds_read_b128 v[202:205], v160 offset:19456
	ds_read_b128 v[206:209], v160 offset:20480
	ds_read_b128 v[218:221], v160 offset:21504
	ds_read_b128 v[226:229], v160 offset:22528
	ds_read_b128 v[230:233], v160 offset:23552
	global_load_lds_dwordx4 v[152:153], off
	s_add_i32 m0, s72, 0x2000
	s_add_u32 s72, s40, 0x40000
	v_lshl_add_u64 v[210:211], s[40:41], 0, v[138:139]
	s_addc_u32 s73, s41, 0
	s_add_i32 s74, s59, s33
	global_load_lds_dwordx4 v[210:211], off
	v_lshl_add_u64 v[234:235], s[72:73], 0, v[134:135]
	s_mov_b32 m0, s74
	v_lshl_add_u64 v[236:237], s[42:43], 0, v[136:137]
	global_load_lds_dwordx4 v[234:235], off
	v_lshl_add_u64 v[234:235], s[72:73], 0, v[138:139]
	s_add_i32 m0, s74, 0x2000
	s_nop 0
	global_load_lds_dwordx4 v[234:235], off
	v_lshl_add_u64 v[234:235], s[42:43], 0, v[132:133]
	s_mov_b32 m0, s37
	s_nop 0
	global_load_lds_dwordx4 v[234:235], off
	s_mov_b32 m0, s44
	s_nop 0
	global_load_lds_dwordx4 v[236:237], off
	s_waitcnt vmcnt(8)
	s_waitcnt lgkmcnt(0)
	s_barrier
	s_setprio 1
	s_waitcnt lgkmcnt(0)
	v_mfma_f32_16x16x32_bf16 v[64:67], v[148:151], v[190:193], v[64:67]
	v_mfma_f32_16x16x32_bf16 v[60:63], v[166:169], v[190:193], v[60:63]
	v_mfma_f32_16x16x32_bf16 v[48:51], v[148:151], v[198:201], v[48:51]
	v_mfma_f32_16x16x32_bf16 v[44:47], v[166:169], v[198:201], v[44:47]
	v_mfma_f32_16x16x32_bf16 v[32:35], v[148:151], v[206:209], v[32:35]
	v_mfma_f32_16x16x32_bf16 v[28:31], v[166:169], v[206:209], v[28:31]
	v_mfma_f32_16x16x32_bf16 v[16:19], v[148:151], v[226:229], v[16:19]
	v_mfma_f32_16x16x32_bf16 v[12:15], v[166:169], v[226:229], v[12:15]
	v_mfma_f32_16x16x32_bf16 v[64:67], v[162:165], v[194:197], v[64:67]
	v_mfma_f32_16x16x32_bf16 v[60:63], v[170:173], v[194:197], v[60:63]
	v_mfma_f32_16x16x32_bf16 v[48:51], v[162:165], v[202:205], v[48:51]
	v_mfma_f32_16x16x32_bf16 v[44:47], v[170:173], v[202:205], v[44:47]
	v_mfma_f32_16x16x32_bf16 v[32:35], v[162:165], v[218:221], v[32:35]
	v_mfma_f32_16x16x32_bf16 v[28:31], v[170:173], v[218:221], v[28:31]
	v_mfma_f32_16x16x32_bf16 v[16:19], v[162:165], v[230:233], v[16:19]
	v_mfma_f32_16x16x32_bf16 v[12:15], v[170:173], v[230:233], v[12:15]
	v_mfma_f32_16x16x32_bf16 v[56:59], v[174:177], v[190:193], v[56:59]
	v_mfma_f32_16x16x32_bf16 v[52:55], v[182:185], v[190:193], v[52:55]
	v_mfma_f32_16x16x32_bf16 v[40:43], v[174:177], v[198:201], v[40:43]
	v_mfma_f32_16x16x32_bf16 v[36:39], v[182:185], v[198:201], v[36:39]
	v_mfma_f32_16x16x32_bf16 v[24:27], v[174:177], v[206:209], v[24:27]
	v_mfma_f32_16x16x32_bf16 v[20:23], v[182:185], v[206:209], v[20:23]
	v_mfma_f32_16x16x32_bf16 v[8:11], v[174:177], v[226:229], v[8:11]
	v_mfma_f32_16x16x32_bf16 v[4:7], v[182:185], v[226:229], v[4:7]
	v_mfma_f32_16x16x32_bf16 v[56:59], v[178:181], v[194:197], v[56:59]
	v_mfma_f32_16x16x32_bf16 v[52:55], v[186:189], v[194:197], v[52:55]
	v_mfma_f32_16x16x32_bf16 v[40:43], v[178:181], v[202:205], v[40:43]
	v_mfma_f32_16x16x32_bf16 v[36:39], v[186:189], v[202:205], v[36:39]
	v_mfma_f32_16x16x32_bf16 v[24:27], v[178:181], v[218:221], v[24:27]
	v_mfma_f32_16x16x32_bf16 v[20:23], v[186:189], v[218:221], v[20:23]
	v_mfma_f32_16x16x32_bf16 v[8:11], v[178:181], v[230:233], v[8:11]
	v_mfma_f32_16x16x32_bf16 v[4:7], v[186:189], v[230:233], v[4:7]
	s_setprio 0
	s_barrier
	s_add_i32 s72, 0, 0x18000
	v_add_u32_e32 v161, s72, v154
	s_add_i32 s73, 0, 0x1c000
	ds_read_b128 v[148:151], v161
	ds_read_b128 v[162:165], v161 offset:1024
	ds_read_b128 v[166:169], v161 offset:2048
	ds_read_b128 v[170:173], v161 offset:3072
	v_add_u32_e32 v161, s73, v154
	ds_read_b128 v[174:177], v161
	ds_read_b128 v[178:181], v161 offset:1024
	ds_read_b128 v[182:185], v161 offset:2048
	ds_read_b128 v[186:189], v161 offset:3072
	s_add_u32 s42, s42, 0x40000
	s_addc_u32 s43, s43, 0
	s_mov_b32 m0, s45
	v_lshl_add_u64 v[238:239], s[42:43], 0, v[132:133]
	ds_read_b128 v[190:193], v160 offset:32768
	ds_read_b128 v[194:197], v160 offset:33792
	ds_read_b128 v[198:201], v160 offset:34816
	ds_read_b128 v[202:205], v160 offset:35840
	ds_read_b128 v[206:209], v160 offset:36864
	ds_read_b128 v[218:221], v160 offset:37888
	ds_read_b128 v[226:229], v160 offset:38912
	ds_read_b128 v[230:233], v160 offset:39936
	global_load_lds_dwordx4 v[238:239], off
	v_lshl_add_u64 v[238:239], s[42:43], 0, v[136:137]
	s_mov_b32 m0, s46
	s_nop 0
	global_load_lds_dwordx4 v[238:239], off
	s_waitcnt vmcnt(8)
	s_waitcnt lgkmcnt(0)
	s_barrier
	s_setprio 1
	s_waitcnt lgkmcnt(0)
	v_mfma_f32_16x16x32_bf16 v[128:131], v[148:151], v[190:193], v[128:131]
	v_mfma_f32_16x16x32_bf16 v[124:127], v[166:169], v[190:193], v[124:127]
	v_mfma_f32_16x16x32_bf16 v[112:115], v[148:151], v[198:201], v[112:115]
	v_mfma_f32_16x16x32_bf16 v[108:111], v[166:169], v[198:201], v[108:111]
	v_mfma_f32_16x16x32_bf16 v[96:99], v[148:151], v[206:209], v[96:99]
	v_mfma_f32_16x16x32_bf16 v[92:95], v[166:169], v[206:209], v[92:95]
	v_mfma_f32_16x16x32_bf16 v[80:83], v[148:151], v[226:229], v[80:83]
	v_mfma_f32_16x16x32_bf16 v[76:79], v[166:169], v[226:229], v[76:79]
	v_mfma_f32_16x16x32_bf16 v[128:131], v[162:165], v[194:197], v[128:131]
	v_mfma_f32_16x16x32_bf16 v[124:127], v[170:173], v[194:197], v[124:127]
	v_mfma_f32_16x16x32_bf16 v[112:115], v[162:165], v[202:205], v[112:115]
	v_mfma_f32_16x16x32_bf16 v[108:111], v[170:173], v[202:205], v[108:111]
	v_mfma_f32_16x16x32_bf16 v[96:99], v[162:165], v[218:221], v[96:99]
	v_mfma_f32_16x16x32_bf16 v[92:95], v[170:173], v[218:221], v[92:95]
	v_mfma_f32_16x16x32_bf16 v[80:83], v[162:165], v[230:233], v[80:83]
	v_mfma_f32_16x16x32_bf16 v[76:79], v[170:173], v[230:233], v[76:79]
	v_mfma_f32_16x16x32_bf16 v[120:123], v[174:177], v[190:193], v[120:123]
	v_mfma_f32_16x16x32_bf16 v[116:119], v[182:185], v[190:193], v[116:119]
	v_mfma_f32_16x16x32_bf16 v[104:107], v[174:177], v[198:201], v[104:107]
	v_mfma_f32_16x16x32_bf16 v[100:103], v[182:185], v[198:201], v[100:103]
	v_mfma_f32_16x16x32_bf16 v[88:91], v[174:177], v[206:209], v[88:91]
	v_mfma_f32_16x16x32_bf16 v[84:87], v[182:185], v[206:209], v[84:87]
	v_mfma_f32_16x16x32_bf16 v[72:75], v[174:177], v[226:229], v[72:75]
	v_mfma_f32_16x16x32_bf16 v[68:71], v[182:185], v[226:229], v[68:71]
	v_mfma_f32_16x16x32_bf16 v[120:123], v[178:181], v[194:197], v[120:123]
	v_mfma_f32_16x16x32_bf16 v[116:119], v[186:189], v[194:197], v[116:119]
	v_mfma_f32_16x16x32_bf16 v[104:107], v[178:181], v[202:205], v[104:107]
	v_mfma_f32_16x16x32_bf16 v[100:103], v[186:189], v[202:205], v[100:103]
	v_mfma_f32_16x16x32_bf16 v[88:91], v[178:181], v[218:221], v[88:91]
	v_mfma_f32_16x16x32_bf16 v[84:87], v[186:189], v[218:221], v[84:87]
	v_mfma_f32_16x16x32_bf16 v[72:75], v[178:181], v[230:233], v[72:75]
	v_mfma_f32_16x16x32_bf16 v[68:71], v[186:189], v[230:233], v[68:71]
	s_setprio 0
	s_barrier
	s_add_i32 s42, s72, s33
	v_lshl_add_u64 v[152:153], v[152:153], 0, s[12:13]
	s_mov_b32 m0, s42
	ds_read_b128 v[190:193], v160 offset:49152
	ds_read_b128 v[194:197], v160 offset:50176
	ds_read_b128 v[198:201], v160 offset:51200
	ds_read_b128 v[202:205], v160 offset:52224
	ds_read_b128 v[206:209], v160 offset:53248
	ds_read_b128 v[218:221], v160 offset:54272
	ds_read_b128 v[226:229], v160 offset:55296
	ds_read_b128 v[230:233], v160 offset:56320
	global_load_lds_dwordx4 v[152:153], off
	s_add_i32 m0, s42, 0x2000
	s_add_u32 s40, s40, 0x40080
	v_lshl_add_u64 v[152:153], v[210:211], 0, s[12:13]
	s_addc_u32 s41, s41, 0
	s_add_i32 s42, s73, s33
	global_load_lds_dwordx4 v[152:153], off
	v_lshl_add_u64 v[152:153], s[40:41], 0, v[134:135]
	s_mov_b32 m0, s42
	s_nop 0
	global_load_lds_dwordx4 v[152:153], off
	v_lshl_add_u64 v[152:153], s[40:41], 0, v[138:139]
	s_add_i32 m0, s42, 0x2000
	s_nop 0
	global_load_lds_dwordx4 v[152:153], off
	v_lshl_add_u64 v[152:153], v[234:235], 0, s[12:13]
	s_mov_b32 m0, s48
	s_nop 0
	global_load_lds_dwordx4 v[152:153], off
	v_lshl_add_u64 v[152:153], v[236:237], 0, s[12:13]
	s_mov_b32 m0, s49
	s_nop 0
	global_load_lds_dwordx4 v[152:153], off
	s_waitcnt vmcnt(8)
	s_waitcnt lgkmcnt(0)
	s_barrier
	s_setprio 1
	s_waitcnt lgkmcnt(0)
	v_mfma_f32_16x16x32_bf16 v[64:67], v[148:151], v[190:193], v[64:67]
	v_mfma_f32_16x16x32_bf16 v[60:63], v[166:169], v[190:193], v[60:63]
	v_mfma_f32_16x16x32_bf16 v[48:51], v[148:151], v[198:201], v[48:51]
	v_mfma_f32_16x16x32_bf16 v[44:47], v[166:169], v[198:201], v[44:47]
	v_mfma_f32_16x16x32_bf16 v[32:35], v[148:151], v[206:209], v[32:35]
	v_mfma_f32_16x16x32_bf16 v[28:31], v[166:169], v[206:209], v[28:31]
	v_mfma_f32_16x16x32_bf16 v[16:19], v[148:151], v[226:229], v[16:19]
	v_mfma_f32_16x16x32_bf16 v[12:15], v[166:169], v[226:229], v[12:15]
	v_mfma_f32_16x16x32_bf16 v[64:67], v[162:165], v[194:197], v[64:67]
	v_mfma_f32_16x16x32_bf16 v[60:63], v[170:173], v[194:197], v[60:63]
	v_mfma_f32_16x16x32_bf16 v[48:51], v[162:165], v[202:205], v[48:51]
	v_mfma_f32_16x16x32_bf16 v[44:47], v[170:173], v[202:205], v[44:47]
	v_mfma_f32_16x16x32_bf16 v[32:35], v[162:165], v[218:221], v[32:35]
	v_mfma_f32_16x16x32_bf16 v[28:31], v[170:173], v[218:221], v[28:31]
	v_mfma_f32_16x16x32_bf16 v[16:19], v[162:165], v[230:233], v[16:19]
	v_mfma_f32_16x16x32_bf16 v[12:15], v[170:173], v[230:233], v[12:15]
	v_mfma_f32_16x16x32_bf16 v[56:59], v[174:177], v[190:193], v[56:59]
	v_mfma_f32_16x16x32_bf16 v[52:55], v[182:185], v[190:193], v[52:55]
	v_mfma_f32_16x16x32_bf16 v[40:43], v[174:177], v[198:201], v[40:43]
	v_mfma_f32_16x16x32_bf16 v[36:39], v[182:185], v[198:201], v[36:39]
	v_mfma_f32_16x16x32_bf16 v[24:27], v[174:177], v[206:209], v[24:27]
	v_mfma_f32_16x16x32_bf16 v[20:23], v[182:185], v[206:209], v[20:23]
	v_mfma_f32_16x16x32_bf16 v[8:11], v[174:177], v[226:229], v[8:11]
	v_mfma_f32_16x16x32_bf16 v[4:7], v[182:185], v[226:229], v[4:7]
	v_mfma_f32_16x16x32_bf16 v[56:59], v[178:181], v[194:197], v[56:59]
	v_mfma_f32_16x16x32_bf16 v[52:55], v[186:189], v[194:197], v[52:55]
	v_mfma_f32_16x16x32_bf16 v[40:43], v[178:181], v[202:205], v[40:43]
	v_mfma_f32_16x16x32_bf16 v[36:39], v[186:189], v[202:205], v[36:39]
	v_mfma_f32_16x16x32_bf16 v[24:27], v[178:181], v[218:221], v[24:27]
	v_mfma_f32_16x16x32_bf16 v[20:23], v[186:189], v[218:221], v[20:23]
	v_mfma_f32_16x16x32_bf16 v[8:11], v[178:181], v[230:233], v[8:11]
	v_mfma_f32_16x16x32_bf16 v[4:7], v[186:189], v[230:233], v[4:7]
	s_setprio 0
	s_barrier
	s_add_i32 s71, s71, 2
	s_add_u32 s38, s38, 0x100
	s_addc_u32 s39, s39, 0
	s_add_u32 s69, s69, 0x100
	s_addc_u32 s70, s70, 0
	s_cmp_gt_u32 s71, 13
	s_cbranch_scc0 .LBB0_820
	s_and_b64 vcc, exec, s[16:17]
	s_cbranch_vccz .LBB0_823
	s_barrier

.LBB0_936:
	v_add_u32_e32 v93, s51, v152
	ds_read_b128 v[154:157], v93
	ds_read_b128 v[158:161], v93 offset:1024
	ds_read_b128 v[166:169], v93 offset:2048
	ds_read_b128 v[170:173], v93 offset:3072
	v_add_u32_e32 v93, s58, v152
	ds_read_b128 v[174:177], v93
	ds_read_b128 v[178:181], v93 offset:1024
	ds_read_b128 v[182:185], v93 offset:2048
	ds_read_b128 v[186:189], v93 offset:3072
	s_add_i32 s67, s34, 2
	s_add_u32 s68, s30, 0x80
	s_addc_u32 s35, s31, 0
	s_cmp_eq_u32 s50, s34
	s_cselect_b32 s34, s6, s68
	s_cselect_b32 s35, s7, s35
	s_cselect_b32 s69, s29, s66
	s_cselect_b32 s68, s28, s65
	v_lshl_add_u64 v[94:95], s[30:31], 0, v[120:121]
	s_add_i32 m0, s42, 0xc000
	ds_read_b128 v[190:193], v153
	ds_read_b128 v[194:197], v153 offset:1024
	ds_read_b128 v[198:201], v153 offset:2048
	ds_read_b128 v[202:205], v153 offset:3072
	ds_read_b128 v[206:209], v153 offset:4096
	ds_read_b128 v[218:221], v153 offset:5120
	ds_read_b128 v[226:229], v153 offset:6144
	ds_read_b128 v[230:233], v153 offset:7168
	global_load_lds_dwordx4 v[94:95], off
	v_lshl_add_u64 v[94:95], s[30:31], 0, v[122:123]
	s_add_i32 m0, s42, 0xe000
	s_nop 0
	global_load_lds_dwordx4 v[94:95], off
	s_waitcnt vmcnt(8)
	s_waitcnt lgkmcnt(0)
	s_barrier
	s_setprio 1
	s_waitcnt lgkmcnt(0)
	v_mfma_f32_16x16x32_bf16 v[148:151], v[154:157], v[190:193], v[148:151]
	v_mfma_f32_16x16x32_bf16 v[144:147], v[166:169], v[190:193], v[144:147]
	v_mfma_f32_16x16x32_bf16 v[128:131], v[154:157], v[198:201], v[128:131]
	v_mfma_f32_16x16x32_bf16 v[124:127], v[166:169], v[198:201], v[124:127]
	v_mfma_f32_16x16x32_bf16 v[104:107], v[154:157], v[206:209], v[104:107]
	v_mfma_f32_16x16x32_bf16 v[94:97], v[166:169], v[206:209], v[96:99]
	v_mfma_f32_16x16x32_bf16 v[80:83], v[154:157], v[226:229], v[80:83]
	v_mfma_f32_16x16x32_bf16 v[76:79], v[166:169], v[226:229], v[76:79]
	v_mfma_f32_16x16x32_bf16 v[148:151], v[158:161], v[194:197], v[148:151]
	v_mfma_f32_16x16x32_bf16 v[144:147], v[170:173], v[194:197], v[144:147]
	v_mfma_f32_16x16x32_bf16 v[128:131], v[158:161], v[202:205], v[128:131]
	v_mfma_f32_16x16x32_bf16 v[124:127], v[170:173], v[202:205], v[124:127]
	v_mfma_f32_16x16x32_bf16 v[104:107], v[158:161], v[218:221], v[104:107]
	v_mfma_f32_16x16x32_bf16 v[94:97], v[170:173], v[218:221], v[94:97]
	v_mfma_f32_16x16x32_bf16 v[80:83], v[158:161], v[230:233], v[80:83]
	v_mfma_f32_16x16x32_bf16 v[76:79], v[170:173], v[230:233], v[76:79]
	v_mfma_f32_16x16x32_bf16 v[140:143], v[174:177], v[190:193], v[140:143]
	v_mfma_f32_16x16x32_bf16 v[136:139], v[182:185], v[190:193], v[136:139]
	v_mfma_f32_16x16x32_bf16 v[116:119], v[174:177], v[198:201], v[116:119]
	v_mfma_f32_16x16x32_bf16 v[108:111], v[182:185], v[198:201], v[108:111]
	v_mfma_f32_16x16x32_bf16 v[88:91], v[174:177], v[206:209], v[88:91]
	v_mfma_f32_16x16x32_bf16 v[84:87], v[182:185], v[206:209], v[84:87]
	v_mfma_f32_16x16x32_bf16 v[72:75], v[174:177], v[226:229], v[72:75]
	v_mfma_f32_16x16x32_bf16 v[68:71], v[182:185], v[226:229], v[68:71]
	v_mfma_f32_16x16x32_bf16 v[140:143], v[178:181], v[194:197], v[140:143]
	v_mfma_f32_16x16x32_bf16 v[136:139], v[186:189], v[194:197], v[136:139]
	v_mfma_f32_16x16x32_bf16 v[116:119], v[178:181], v[202:205], v[116:119]
	v_mfma_f32_16x16x32_bf16 v[108:111], v[186:189], v[202:205], v[108:111]
	v_mfma_f32_16x16x32_bf16 v[88:91], v[178:181], v[218:221], v[88:91]
	v_mfma_f32_16x16x32_bf16 v[84:87], v[186:189], v[218:221], v[84:87]
	v_mfma_f32_16x16x32_bf16 v[72:75], v[178:181], v[230:233], v[72:75]
	v_mfma_f32_16x16x32_bf16 v[68:71], v[186:189], v[230:233], v[68:71]
	s_setprio 0
	s_barrier
	s_add_i32 s70, s51, s38
	v_lshl_add_u64 v[162:163], s[68:69], 0, v[102:103]
	s_mov_b32 m0, s70
	ds_read_b128 v[190:193], v153 offset:16384
	ds_read_b128 v[194:197], v153 offset:17408
	ds_read_b128 v[198:201], v153 offset:18432
	ds_read_b128 v[202:205], v153 offset:19456
	ds_read_b128 v[206:209], v153 offset:20480
	ds_read_b128 v[218:221], v153 offset:21504
	ds_read_b128 v[226:229], v153 offset:22528
	ds_read_b128 v[230:233], v153 offset:23552
	global_load_lds_dwordx4 v[162:163], off
	s_add_i32 m0, s70, 0x2000
	v_lshl_add_u64 v[210:211], s[68:69], 0, v[114:115]
	s_add_u32 s68, s68, s16
	s_addc_u32 s69, s69, s17
	s_add_i32 s70, s58, s38
	global_load_lds_dwordx4 v[210:211], off
	v_lshl_add_u64 v[234:235], s[68:69], 0, v[102:103]
	s_mov_b32 m0, s70
	v_lshl_add_u64 v[236:237], s[68:69], 0, v[114:115]
	global_load_lds_dwordx4 v[234:235], off
	s_add_i32 m0, s70, 0x2000
	v_lshl_add_u64 v[238:239], s[34:35], 0, v[100:101]
	global_load_lds_dwordx4 v[236:237], off
	s_mov_b32 m0, s42
	v_lshl_add_u64 v[240:241], s[34:35], 0, v[112:113]
	global_load_lds_dwordx4 v[238:239], off
	s_mov_b32 m0, s43
	s_nop 0
	global_load_lds_dwordx4 v[240:241], off
	s_waitcnt vmcnt(8)
	s_waitcnt lgkmcnt(0)
	s_barrier
	s_setprio 1
	s_waitcnt lgkmcnt(0)
	v_mfma_f32_16x16x32_bf16 v[64:67], v[154:157], v[190:193], v[64:67]
	v_mfma_f32_16x16x32_bf16 v[60:63], v[166:169], v[190:193], v[60:63]
	v_mfma_f32_16x16x32_bf16 v[48:51], v[154:157], v[198:201], v[48:51]
	v_mfma_f32_16x16x32_bf16 v[44:47], v[166:169], v[198:201], v[44:47]
	v_mfma_f32_16x16x32_bf16 v[32:35], v[154:157], v[206:209], v[32:35]
	v_mfma_f32_16x16x32_bf16 v[28:31], v[166:169], v[206:209], v[28:31]
	v_mfma_f32_16x16x32_bf16 v[16:19], v[154:157], v[226:229], v[16:19]
	v_mfma_f32_16x16x32_bf16 v[12:15], v[166:169], v[226:229], v[12:15]
	v_mfma_f32_16x16x32_bf16 v[64:67], v[158:161], v[194:197], v[64:67]
	v_mfma_f32_16x16x32_bf16 v[60:63], v[170:173], v[194:197], v[60:63]
	v_mfma_f32_16x16x32_bf16 v[48:51], v[158:161], v[202:205], v[48:51]
	v_mfma_f32_16x16x32_bf16 v[44:47], v[170:173], v[202:205], v[44:47]
	v_mfma_f32_16x16x32_bf16 v[32:35], v[158:161], v[218:221], v[32:35]
	v_mfma_f32_16x16x32_bf16 v[28:31], v[170:173], v[218:221], v[28:31]
	v_mfma_f32_16x16x32_bf16 v[16:19], v[158:161], v[230:233], v[16:19]
	v_mfma_f32_16x16x32_bf16 v[12:15], v[170:173], v[230:233], v[12:15]
	v_mfma_f32_16x16x32_bf16 v[56:59], v[174:177], v[190:193], v[56:59]
	v_mfma_f32_16x16x32_bf16 v[52:55], v[182:185], v[190:193], v[52:55]
	v_mfma_f32_16x16x32_bf16 v[40:43], v[174:177], v[198:201], v[40:43]
	v_mfma_f32_16x16x32_bf16 v[36:39], v[182:185], v[198:201], v[36:39]
	v_mfma_f32_16x16x32_bf16 v[24:27], v[174:177], v[206:209], v[24:27]
	v_mfma_f32_16x16x32_bf16 v[20:23], v[182:185], v[206:209], v[20:23]
	v_mfma_f32_16x16x32_bf16 v[8:11], v[174:177], v[226:229], v[8:11]
	v_mfma_f32_16x16x32_bf16 v[4:7], v[182:185], v[226:229], v[4:7]
	v_mfma_f32_16x16x32_bf16 v[56:59], v[178:181], v[194:197], v[56:59]
	v_mfma_f32_16x16x32_bf16 v[52:55], v[186:189], v[194:197], v[52:55]
	v_mfma_f32_16x16x32_bf16 v[40:43], v[178:181], v[202:205], v[40:43]
	v_mfma_f32_16x16x32_bf16 v[36:39], v[186:189], v[202:205], v[36:39]
	v_mfma_f32_16x16x32_bf16 v[24:27], v[178:181], v[218:221], v[24:27]
	v_mfma_f32_16x16x32_bf16 v[20:23], v[186:189], v[218:221], v[20:23]
	v_mfma_f32_16x16x32_bf16 v[8:11], v[178:181], v[230:233], v[8:11]
	v_mfma_f32_16x16x32_bf16 v[4:7], v[186:189], v[230:233], v[4:7]
	s_setprio 0
	s_barrier
	s_add_i32 s68, 0, 0x18000
	v_add_u32_e32 v93, s68, v152
	s_add_i32 s69, 0, 0x1c000
	ds_read_b128 v[154:157], v93
	ds_read_b128 v[158:161], v93 offset:1024
	ds_read_b128 v[166:169], v93 offset:2048
	ds_read_b128 v[170:173], v93 offset:3072
	v_add_u32_e32 v93, s69, v152
	ds_read_b128 v[174:177], v93
	ds_read_b128 v[178:181], v93 offset:1024
	ds_read_b128 v[182:185], v93 offset:2048
	ds_read_b128 v[186:189], v93 offset:3072
	s_add_u32 s34, s34, s16
	s_addc_u32 s35, s35, s17
	s_mov_b32 m0, s44
	v_lshl_add_u64 v[98:99], s[34:35], 0, v[100:101]
	ds_read_b128 v[190:193], v153 offset:32768
	ds_read_b128 v[194:197], v153 offset:33792
	ds_read_b128 v[198:201], v153 offset:34816
	ds_read_b128 v[202:205], v153 offset:35840
	ds_read_b128 v[206:209], v153 offset:36864
	ds_read_b128 v[218:221], v153 offset:37888
	ds_read_b128 v[226:229], v153 offset:38912
	ds_read_b128 v[230:233], v153 offset:39936
	global_load_lds_dwordx4 v[98:99], off
	v_lshl_add_u64 v[98:99], s[34:35], 0, v[112:113]
	s_mov_b32 m0, s45
	s_nop 0
	global_load_lds_dwordx4 v[98:99], off
	s_waitcnt vmcnt(8)
	s_waitcnt lgkmcnt(0)
	s_barrier
	s_setprio 1
	s_waitcnt lgkmcnt(0)
	v_mfma_f32_16x16x32_bf16 v[148:151], v[154:157], v[190:193], v[148:151]
	v_mfma_f32_16x16x32_bf16 v[144:147], v[166:169], v[190:193], v[144:147]
	v_mfma_f32_16x16x32_bf16 v[128:131], v[154:157], v[198:201], v[128:131]
	v_mfma_f32_16x16x32_bf16 v[124:127], v[166:169], v[198:201], v[124:127]
	v_mfma_f32_16x16x32_bf16 v[104:107], v[154:157], v[206:209], v[104:107]
	v_mfma_f32_16x16x32_bf16 v[94:97], v[166:169], v[206:209], v[94:97]
	v_mfma_f32_16x16x32_bf16 v[80:83], v[154:157], v[226:229], v[80:83]
	v_mfma_f32_16x16x32_bf16 v[76:79], v[166:169], v[226:229], v[76:79]
	v_mfma_f32_16x16x32_bf16 v[148:151], v[158:161], v[194:197], v[148:151]
	v_mfma_f32_16x16x32_bf16 v[144:147], v[170:173], v[194:197], v[144:147]
	v_mfma_f32_16x16x32_bf16 v[128:131], v[158:161], v[202:205], v[128:131]
	v_mfma_f32_16x16x32_bf16 v[124:127], v[170:173], v[202:205], v[124:127]
	v_mfma_f32_16x16x32_bf16 v[104:107], v[158:161], v[218:221], v[104:107]
	v_mfma_f32_16x16x32_bf16 v[96:99], v[170:173], v[218:221], v[94:97]
	v_mfma_f32_16x16x32_bf16 v[80:83], v[158:161], v[230:233], v[80:83]
	v_mfma_f32_16x16x32_bf16 v[76:79], v[170:173], v[230:233], v[76:79]
	v_mfma_f32_16x16x32_bf16 v[140:143], v[174:177], v[190:193], v[140:143]
	v_mfma_f32_16x16x32_bf16 v[136:139], v[182:185], v[190:193], v[136:139]
	v_mfma_f32_16x16x32_bf16 v[116:119], v[174:177], v[198:201], v[116:119]
	v_mfma_f32_16x16x32_bf16 v[108:111], v[182:185], v[198:201], v[108:111]
	v_mfma_f32_16x16x32_bf16 v[88:91], v[174:177], v[206:209], v[88:91]
	v_mfma_f32_16x16x32_bf16 v[84:87], v[182:185], v[206:209], v[84:87]
	v_mfma_f32_16x16x32_bf16 v[72:75], v[174:177], v[226:229], v[72:75]
	v_mfma_f32_16x16x32_bf16 v[68:71], v[182:185], v[226:229], v[68:71]
	v_mfma_f32_16x16x32_bf16 v[140:143], v[178:181], v[194:197], v[140:143]
	v_mfma_f32_16x16x32_bf16 v[136:139], v[186:189], v[194:197], v[136:139]
	v_mfma_f32_16x16x32_bf16 v[116:119], v[178:181], v[202:205], v[116:119]
	v_mfma_f32_16x16x32_bf16 v[108:111], v[186:189], v[202:205], v[108:111]
	v_mfma_f32_16x16x32_bf16 v[88:91], v[178:181], v[218:221], v[88:91]
	v_mfma_f32_16x16x32_bf16 v[84:87], v[186:189], v[218:221], v[84:87]
	v_mfma_f32_16x16x32_bf16 v[72:75], v[178:181], v[230:233], v[72:75]
	v_mfma_f32_16x16x32_bf16 v[68:71], v[186:189], v[230:233], v[68:71]
	s_setprio 0
	s_barrier
	s_add_i32 s34, s68, s38
	v_lshl_add_u64 v[94:95], v[162:163], 0, s[24:25]
	s_mov_b32 m0, s34
	ds_read_b128 v[190:193], v153 offset:49152
	ds_read_b128 v[194:197], v153 offset:50176
	ds_read_b128 v[198:201], v153 offset:51200
	ds_read_b128 v[202:205], v153 offset:52224
	ds_read_b128 v[206:209], v153 offset:53248
	ds_read_b128 v[218:221], v153 offset:54272
	ds_read_b128 v[226:229], v153 offset:55296
	ds_read_b128 v[230:233], v153 offset:56320
	global_load_lds_dwordx4 v[94:95], off
	v_lshl_add_u64 v[94:95], v[210:211], 0, s[24:25]
	s_add_i32 m0, s34, 0x2000
	s_add_i32 s34, s69, s38
	global_load_lds_dwordx4 v[94:95], off
	v_lshl_add_u64 v[94:95], v[234:235], 0, s[24:25]
	s_mov_b32 m0, s34
	s_nop 0
	global_load_lds_dwordx4 v[94:95], off
	v_lshl_add_u64 v[94:95], v[236:237], 0, s[24:25]
	s_add_i32 m0, s34, 0x2000
	s_nop 0
	global_load_lds_dwordx4 v[94:95], off
	v_lshl_add_u64 v[94:95], v[238:239], 0, s[24:25]
	s_mov_b32 m0, s46
	s_nop 0
	global_load_lds_dwordx4 v[94:95], off
	v_lshl_add_u64 v[94:95], v[240:241], 0, s[24:25]
	s_mov_b32 m0, s47
	s_nop 0
	global_load_lds_dwordx4 v[94:95], off
	s_waitcnt vmcnt(8)
	s_waitcnt lgkmcnt(0)
	s_barrier
	s_setprio 1
	s_waitcnt lgkmcnt(0)
	v_mfma_f32_16x16x32_bf16 v[64:67], v[154:157], v[190:193], v[64:67]
	v_mfma_f32_16x16x32_bf16 v[60:63], v[166:169], v[190:193], v[60:63]
	v_mfma_f32_16x16x32_bf16 v[48:51], v[154:157], v[198:201], v[48:51]
	v_mfma_f32_16x16x32_bf16 v[44:47], v[166:169], v[198:201], v[44:47]
	v_mfma_f32_16x16x32_bf16 v[32:35], v[154:157], v[206:209], v[32:35]
	v_mfma_f32_16x16x32_bf16 v[28:31], v[166:169], v[206:209], v[28:31]
	v_mfma_f32_16x16x32_bf16 v[16:19], v[154:157], v[226:229], v[16:19]
	v_mfma_f32_16x16x32_bf16 v[12:15], v[166:169], v[226:229], v[12:15]
	v_mfma_f32_16x16x32_bf16 v[64:67], v[158:161], v[194:197], v[64:67]
	v_mfma_f32_16x16x32_bf16 v[60:63], v[170:173], v[194:197], v[60:63]
	v_mfma_f32_16x16x32_bf16 v[48:51], v[158:161], v[202:205], v[48:51]
	v_mfma_f32_16x16x32_bf16 v[44:47], v[170:173], v[202:205], v[44:47]
	v_mfma_f32_16x16x32_bf16 v[32:35], v[158:161], v[218:221], v[32:35]
	v_mfma_f32_16x16x32_bf16 v[28:31], v[170:173], v[218:221], v[28:31]
	v_mfma_f32_16x16x32_bf16 v[16:19], v[158:161], v[230:233], v[16:19]
	v_mfma_f32_16x16x32_bf16 v[12:15], v[170:173], v[230:233], v[12:15]
	v_mfma_f32_16x16x32_bf16 v[56:59], v[174:177], v[190:193], v[56:59]
	v_mfma_f32_16x16x32_bf16 v[52:55], v[182:185], v[190:193], v[52:55]
	v_mfma_f32_16x16x32_bf16 v[40:43], v[174:177], v[198:201], v[40:43]
	v_mfma_f32_16x16x32_bf16 v[36:39], v[182:185], v[198:201], v[36:39]
	v_mfma_f32_16x16x32_bf16 v[24:27], v[174:177], v[206:209], v[24:27]
	v_mfma_f32_16x16x32_bf16 v[20:23], v[182:185], v[206:209], v[20:23]
	v_mfma_f32_16x16x32_bf16 v[8:11], v[174:177], v[226:229], v[8:11]
	v_mfma_f32_16x16x32_bf16 v[4:7], v[182:185], v[226:229], v[4:7]
	v_mfma_f32_16x16x32_bf16 v[56:59], v[178:181], v[194:197], v[56:59]
	v_mfma_f32_16x16x32_bf16 v[52:55], v[186:189], v[194:197], v[52:55]
	v_mfma_f32_16x16x32_bf16 v[40:43], v[178:181], v[202:205], v[40:43]
	v_mfma_f32_16x16x32_bf16 v[36:39], v[186:189], v[202:205], v[36:39]
	v_mfma_f32_16x16x32_bf16 v[24:27], v[178:181], v[218:221], v[24:27]
	v_mfma_f32_16x16x32_bf16 v[20:23], v[186:189], v[218:221], v[20:23]
	v_mfma_f32_16x16x32_bf16 v[8:11], v[178:181], v[230:233], v[8:11]
	v_mfma_f32_16x16x32_bf16 v[4:7], v[186:189], v[230:233], v[4:7]
	s_setprio 0
	s_barrier
	s_add_u32 s30, s30, 0x100
	s_addc_u32 s31, s31, 0
	s_add_u32 s65, s65, 0x100
	s_addc_u32 s66, s66, 0
	s_cmp_ge_i32 s67, s49
	s_mov_b32 s34, s67
	s_cbranch_scc0 .LBB0_936

.LBB0_1116:
	ds_read_b128 v[148:151], v160
	ds_read_b128 v[152:155], v160 offset:1024
	ds_read_b128 v[166:169], v160 offset:2048
	ds_read_b128 v[170:173], v160 offset:3072
	ds_read_b128 v[174:177], v161
	ds_read_b128 v[178:181], v161 offset:1024
	ds_read_b128 v[182:185], v161 offset:2048
	ds_read_b128 v[186:189], v161 offset:3072
	s_add_u32 s48, s4, 0xfffc0080
	s_addc_u32 s49, s5, -1
	s_cmp_eq_u32 s71, 12
	s_cselect_b32 s59, s39, s49
	s_cselect_b32 s58, s45, s48
	s_cselect_b32 s49, s37, s70
	s_cselect_b32 s48, s60, s61
	v_lshl_add_u64 v[210:211], s[4:5], 0, v[140:141]
	s_add_i32 m0, s47, 0xc000
	ds_read_b128 v[190:193], v162
	ds_read_b128 v[194:197], v162 offset:1024
	ds_read_b128 v[198:201], v162 offset:2048
	ds_read_b128 v[202:205], v162 offset:3072
	ds_read_b128 v[206:209], v162 offset:4096
	ds_read_b128 v[226:229], v162 offset:5120
	ds_read_b128 v[230:233], v162 offset:6144
	ds_read_b128 v[234:237], v162 offset:7168
	global_load_lds_dwordx4 v[210:211], off
	v_lshl_add_u64 v[210:211], s[4:5], 0, v[142:143]
	s_add_i32 m0, s47, 0xe000
	s_nop 0
	global_load_lds_dwordx4 v[210:211], off
	s_waitcnt vmcnt(8)
	s_waitcnt lgkmcnt(0)
	s_barrier
	s_setprio 1
	s_waitcnt lgkmcnt(0)
	v_mfma_f32_16x16x32_bf16 v[128:131], v[148:151], v[190:193], v[128:131]
	v_mfma_f32_16x16x32_bf16 v[124:127], v[166:169], v[190:193], v[124:127]
	v_mfma_f32_16x16x32_bf16 v[112:115], v[148:151], v[198:201], v[112:115]
	v_mfma_f32_16x16x32_bf16 v[108:111], v[166:169], v[198:201], v[108:111]
	v_mfma_f32_16x16x32_bf16 v[96:99], v[148:151], v[206:209], v[96:99]
	v_mfma_f32_16x16x32_bf16 v[92:95], v[166:169], v[206:209], v[92:95]
	v_mfma_f32_16x16x32_bf16 v[80:83], v[148:151], v[230:233], v[80:83]
	v_mfma_f32_16x16x32_bf16 v[76:79], v[166:169], v[230:233], v[76:79]
	v_mfma_f32_16x16x32_bf16 v[128:131], v[152:155], v[194:197], v[128:131]
	v_mfma_f32_16x16x32_bf16 v[124:127], v[170:173], v[194:197], v[124:127]
	v_mfma_f32_16x16x32_bf16 v[112:115], v[152:155], v[202:205], v[112:115]
	v_mfma_f32_16x16x32_bf16 v[108:111], v[170:173], v[202:205], v[108:111]
	v_mfma_f32_16x16x32_bf16 v[96:99], v[152:155], v[226:229], v[96:99]
	v_mfma_f32_16x16x32_bf16 v[92:95], v[170:173], v[226:229], v[92:95]
	v_mfma_f32_16x16x32_bf16 v[80:83], v[152:155], v[234:237], v[80:83]
	v_mfma_f32_16x16x32_bf16 v[76:79], v[170:173], v[234:237], v[76:79]
	v_mfma_f32_16x16x32_bf16 v[120:123], v[174:177], v[190:193], v[120:123]
	v_mfma_f32_16x16x32_bf16 v[116:119], v[182:185], v[190:193], v[116:119]
	v_mfma_f32_16x16x32_bf16 v[104:107], v[174:177], v[198:201], v[104:107]
	v_mfma_f32_16x16x32_bf16 v[100:103], v[182:185], v[198:201], v[100:103]
	v_mfma_f32_16x16x32_bf16 v[88:91], v[174:177], v[206:209], v[88:91]
	v_mfma_f32_16x16x32_bf16 v[84:87], v[182:185], v[206:209], v[84:87]
	v_mfma_f32_16x16x32_bf16 v[72:75], v[174:177], v[230:233], v[72:75]
	v_mfma_f32_16x16x32_bf16 v[68:71], v[182:185], v[230:233], v[68:71]
	v_mfma_f32_16x16x32_bf16 v[120:123], v[178:181], v[194:197], v[120:123]
	v_mfma_f32_16x16x32_bf16 v[116:119], v[186:189], v[194:197], v[116:119]
	v_mfma_f32_16x16x32_bf16 v[104:107], v[178:181], v[202:205], v[104:107]
	v_mfma_f32_16x16x32_bf16 v[100:103], v[186:189], v[202:205], v[100:103]
	v_mfma_f32_16x16x32_bf16 v[88:91], v[178:181], v[226:229], v[88:91]
	v_mfma_f32_16x16x32_bf16 v[84:87], v[186:189], v[226:229], v[84:87]
	v_mfma_f32_16x16x32_bf16 v[72:75], v[178:181], v[234:237], v[72:75]
	v_mfma_f32_16x16x32_bf16 v[68:71], v[186:189], v[234:237], v[68:71]
	s_setprio 0
	s_barrier
	s_add_i32 s72, s78, s3
	v_lshl_add_u64 v[210:211], s[48:49], 0, v[134:135]
	s_mov_b32 m0, s72
	ds_read_b128 v[190:193], v162 offset:16384
	ds_read_b128 v[194:197], v162 offset:17408
	ds_read_b128 v[198:201], v162 offset:18432
	ds_read_b128 v[202:205], v162 offset:19456
	ds_read_b128 v[206:209], v162 offset:20480
	ds_read_b128 v[226:229], v162 offset:21504
	ds_read_b128 v[230:233], v162 offset:22528
	ds_read_b128 v[234:237], v162 offset:23552
	global_load_lds_dwordx4 v[210:211], off
	s_add_i32 m0, s72, 0x2000
	s_add_u32 s72, s48, 0x40000
	v_lshl_add_u64 v[220:221], s[48:49], 0, v[138:139]
	s_addc_u32 s73, s49, 0
	s_add_i32 s74, s79, s3
	global_load_lds_dwordx4 v[220:221], off
	v_lshl_add_u64 v[238:239], s[72:73], 0, v[134:135]
	s_mov_b32 m0, s74
	v_lshl_add_u64 v[240:241], s[58:59], 0, v[136:137]
	global_load_lds_dwordx4 v[238:239], off
	v_lshl_add_u64 v[238:239], s[72:73], 0, v[138:139]
	s_add_i32 m0, s74, 0x2000
	s_nop 0
	global_load_lds_dwordx4 v[238:239], off
	v_lshl_add_u64 v[238:239], s[58:59], 0, v[132:133]
	s_mov_b32 m0, s47
	s_nop 0
	global_load_lds_dwordx4 v[238:239], off
	s_mov_b32 m0, s51
	s_nop 0
	global_load_lds_dwordx4 v[240:241], off
	s_waitcnt vmcnt(8)
	s_waitcnt lgkmcnt(0)
	s_barrier
	s_setprio 1
	s_waitcnt lgkmcnt(0)
	v_mfma_f32_16x16x32_bf16 v[64:67], v[148:151], v[190:193], v[64:67]
	v_mfma_f32_16x16x32_bf16 v[60:63], v[166:169], v[190:193], v[60:63]
	v_mfma_f32_16x16x32_bf16 v[48:51], v[148:151], v[198:201], v[48:51]
	v_mfma_f32_16x16x32_bf16 v[44:47], v[166:169], v[198:201], v[44:47]
	v_mfma_f32_16x16x32_bf16 v[32:35], v[148:151], v[206:209], v[32:35]
	v_mfma_f32_16x16x32_bf16 v[28:31], v[166:169], v[206:209], v[28:31]
	v_mfma_f32_16x16x32_bf16 v[16:19], v[148:151], v[230:233], v[16:19]
	v_mfma_f32_16x16x32_bf16 v[12:15], v[166:169], v[230:233], v[12:15]
	v_mfma_f32_16x16x32_bf16 v[64:67], v[152:155], v[194:197], v[64:67]
	v_mfma_f32_16x16x32_bf16 v[60:63], v[170:173], v[194:197], v[60:63]
	v_mfma_f32_16x16x32_bf16 v[48:51], v[152:155], v[202:205], v[48:51]
	v_mfma_f32_16x16x32_bf16 v[44:47], v[170:173], v[202:205], v[44:47]
	v_mfma_f32_16x16x32_bf16 v[32:35], v[152:155], v[226:229], v[32:35]
	v_mfma_f32_16x16x32_bf16 v[28:31], v[170:173], v[226:229], v[28:31]
	v_mfma_f32_16x16x32_bf16 v[16:19], v[152:155], v[234:237], v[16:19]
	v_mfma_f32_16x16x32_bf16 v[12:15], v[170:173], v[234:237], v[12:15]
	v_mfma_f32_16x16x32_bf16 v[56:59], v[174:177], v[190:193], v[56:59]
	v_mfma_f32_16x16x32_bf16 v[52:55], v[182:185], v[190:193], v[52:55]
	v_mfma_f32_16x16x32_bf16 v[40:43], v[174:177], v[198:201], v[40:43]
	v_mfma_f32_16x16x32_bf16 v[36:39], v[182:185], v[198:201], v[36:39]
	v_mfma_f32_16x16x32_bf16 v[24:27], v[174:177], v[206:209], v[24:27]
	v_mfma_f32_16x16x32_bf16 v[20:23], v[182:185], v[206:209], v[20:23]
	v_mfma_f32_16x16x32_bf16 v[8:11], v[174:177], v[230:233], v[8:11]
	v_mfma_f32_16x16x32_bf16 v[4:7], v[182:185], v[230:233], v[4:7]
	v_mfma_f32_16x16x32_bf16 v[56:59], v[178:181], v[194:197], v[56:59]
	v_mfma_f32_16x16x32_bf16 v[52:55], v[186:189], v[194:197], v[52:55]
	v_mfma_f32_16x16x32_bf16 v[40:43], v[178:181], v[202:205], v[40:43]
	v_mfma_f32_16x16x32_bf16 v[36:39], v[186:189], v[202:205], v[36:39]
	v_mfma_f32_16x16x32_bf16 v[24:27], v[178:181], v[226:229], v[24:27]
	v_mfma_f32_16x16x32_bf16 v[20:23], v[186:189], v[226:229], v[20:23]
	v_mfma_f32_16x16x32_bf16 v[8:11], v[178:181], v[234:237], v[8:11]
	v_mfma_f32_16x16x32_bf16 v[4:7], v[186:189], v[234:237], v[4:7]
	s_setprio 0
	s_barrier
	s_add_i32 s72, 0, 0x18000
	v_add_u32_e32 v165, s72, v3
	s_add_i32 s73, 0, 0x1c000
	ds_read_b128 v[148:151], v165
	ds_read_b128 v[152:155], v165 offset:1024
	ds_read_b128 v[166:169], v165 offset:2048
	ds_read_b128 v[170:173], v165 offset:3072
	v_add_u32_e32 v165, s73, v3
	ds_read_b128 v[174:177], v165
	ds_read_b128 v[178:181], v165 offset:1024
	ds_read_b128 v[182:185], v165 offset:2048
	ds_read_b128 v[186:189], v165 offset:3072
	s_add_u32 s58, s58, 0x40000
	s_addc_u32 s59, s59, 0
	s_mov_b32 m0, s64
	v_lshl_add_u64 v[242:243], s[58:59], 0, v[132:133]
	ds_read_b128 v[190:193], v162 offset:32768
	ds_read_b128 v[194:197], v162 offset:33792
	ds_read_b128 v[198:201], v162 offset:34816
	ds_read_b128 v[202:205], v162 offset:35840
	ds_read_b128 v[206:209], v162 offset:36864
	ds_read_b128 v[226:229], v162 offset:37888
	ds_read_b128 v[230:233], v162 offset:38912
	ds_read_b128 v[234:237], v162 offset:39936
	global_load_lds_dwordx4 v[242:243], off
	v_lshl_add_u64 v[242:243], s[58:59], 0, v[136:137]
	s_mov_b32 m0, s65
	s_nop 0
	global_load_lds_dwordx4 v[242:243], off
	s_waitcnt vmcnt(8)
	s_waitcnt lgkmcnt(0)
	s_barrier
	s_setprio 1
	s_waitcnt lgkmcnt(0)
	v_mfma_f32_16x16x32_bf16 v[128:131], v[148:151], v[190:193], v[128:131]
	v_mfma_f32_16x16x32_bf16 v[124:127], v[166:169], v[190:193], v[124:127]
	v_mfma_f32_16x16x32_bf16 v[112:115], v[148:151], v[198:201], v[112:115]
	v_mfma_f32_16x16x32_bf16 v[108:111], v[166:169], v[198:201], v[108:111]
	v_mfma_f32_16x16x32_bf16 v[96:99], v[148:151], v[206:209], v[96:99]
	v_mfma_f32_16x16x32_bf16 v[92:95], v[166:169], v[206:209], v[92:95]
	v_mfma_f32_16x16x32_bf16 v[80:83], v[148:151], v[230:233], v[80:83]
	v_mfma_f32_16x16x32_bf16 v[76:79], v[166:169], v[230:233], v[76:79]
	v_mfma_f32_16x16x32_bf16 v[128:131], v[152:155], v[194:197], v[128:131]
	v_mfma_f32_16x16x32_bf16 v[124:127], v[170:173], v[194:197], v[124:127]
	v_mfma_f32_16x16x32_bf16 v[112:115], v[152:155], v[202:205], v[112:115]
	v_mfma_f32_16x16x32_bf16 v[108:111], v[170:173], v[202:205], v[108:111]
	v_mfma_f32_16x16x32_bf16 v[96:99], v[152:155], v[226:229], v[96:99]
	v_mfma_f32_16x16x32_bf16 v[92:95], v[170:173], v[226:229], v[92:95]
	v_mfma_f32_16x16x32_bf16 v[80:83], v[152:155], v[234:237], v[80:83]
	v_mfma_f32_16x16x32_bf16 v[76:79], v[170:173], v[234:237], v[76:79]
	v_mfma_f32_16x16x32_bf16 v[120:123], v[174:177], v[190:193], v[120:123]
	v_mfma_f32_16x16x32_bf16 v[116:119], v[182:185], v[190:193], v[116:119]
	v_mfma_f32_16x16x32_bf16 v[104:107], v[174:177], v[198:201], v[104:107]
	v_mfma_f32_16x16x32_bf16 v[100:103], v[182:185], v[198:201], v[100:103]
	v_mfma_f32_16x16x32_bf16 v[88:91], v[174:177], v[206:209], v[88:91]
	v_mfma_f32_16x16x32_bf16 v[84:87], v[182:185], v[206:209], v[84:87]
	v_mfma_f32_16x16x32_bf16 v[72:75], v[174:177], v[230:233], v[72:75]
	v_mfma_f32_16x16x32_bf16 v[68:71], v[182:185], v[230:233], v[68:71]
	v_mfma_f32_16x16x32_bf16 v[120:123], v[178:181], v[194:197], v[120:123]
	v_mfma_f32_16x16x32_bf16 v[116:119], v[186:189], v[194:197], v[116:119]
	v_mfma_f32_16x16x32_bf16 v[104:107], v[178:181], v[202:205], v[104:107]
	v_mfma_f32_16x16x32_bf16 v[100:103], v[186:189], v[202:205], v[100:103]
	v_mfma_f32_16x16x32_bf16 v[88:91], v[178:181], v[226:229], v[88:91]
	v_mfma_f32_16x16x32_bf16 v[84:87], v[186:189], v[226:229], v[84:87]
	v_mfma_f32_16x16x32_bf16 v[72:75], v[178:181], v[234:237], v[72:75]
	v_mfma_f32_16x16x32_bf16 v[68:71], v[186:189], v[234:237], v[68:71]
	s_setprio 0
	s_barrier
	s_add_i32 s58, s72, s3
	v_lshl_add_u64 v[210:211], v[210:211], 0, s[22:23]
	s_mov_b32 m0, s58
	ds_read_b128 v[190:193], v162 offset:49152
	ds_read_b128 v[194:197], v162 offset:50176
	ds_read_b128 v[198:201], v162 offset:51200
	ds_read_b128 v[202:205], v162 offset:52224
	ds_read_b128 v[206:209], v162 offset:53248
	ds_read_b128 v[226:229], v162 offset:54272
	ds_read_b128 v[230:233], v162 offset:55296
	ds_read_b128 v[234:237], v162 offset:56320
	global_load_lds_dwordx4 v[210:211], off
	s_add_i32 m0, s58, 0x2000
	s_add_u32 s48, s48, 0x40080
	v_lshl_add_u64 v[210:211], v[220:221], 0, s[22:23]
	s_addc_u32 s49, s49, 0
	s_add_i32 s58, s73, s3
	global_load_lds_dwordx4 v[210:211], off
	v_lshl_add_u64 v[210:211], s[48:49], 0, v[134:135]
	s_mov_b32 m0, s58
	s_nop 0
	global_load_lds_dwordx4 v[210:211], off
	v_lshl_add_u64 v[210:211], s[48:49], 0, v[138:139]
	s_add_i32 m0, s58, 0x2000
	s_nop 0
	global_load_lds_dwordx4 v[210:211], off
	v_lshl_add_u64 v[210:211], v[238:239], 0, s[22:23]
	s_mov_b32 m0, s68
	s_nop 0
	global_load_lds_dwordx4 v[210:211], off
	v_lshl_add_u64 v[210:211], v[240:241], 0, s[22:23]
	s_mov_b32 m0, s69
	s_nop 0
	global_load_lds_dwordx4 v[210:211], off
	s_waitcnt vmcnt(8)
	s_waitcnt lgkmcnt(0)
	s_barrier
	s_setprio 1
	s_waitcnt lgkmcnt(0)
	v_mfma_f32_16x16x32_bf16 v[64:67], v[148:151], v[190:193], v[64:67]
	v_mfma_f32_16x16x32_bf16 v[60:63], v[166:169], v[190:193], v[60:63]
	v_mfma_f32_16x16x32_bf16 v[48:51], v[148:151], v[198:201], v[48:51]
	v_mfma_f32_16x16x32_bf16 v[44:47], v[166:169], v[198:201], v[44:47]
	v_mfma_f32_16x16x32_bf16 v[32:35], v[148:151], v[206:209], v[32:35]
	v_mfma_f32_16x16x32_bf16 v[28:31], v[166:169], v[206:209], v[28:31]
	v_mfma_f32_16x16x32_bf16 v[16:19], v[148:151], v[230:233], v[16:19]
	v_mfma_f32_16x16x32_bf16 v[12:15], v[166:169], v[230:233], v[12:15]
	v_mfma_f32_16x16x32_bf16 v[64:67], v[152:155], v[194:197], v[64:67]
	v_mfma_f32_16x16x32_bf16 v[60:63], v[170:173], v[194:197], v[60:63]
	v_mfma_f32_16x16x32_bf16 v[48:51], v[152:155], v[202:205], v[48:51]
	v_mfma_f32_16x16x32_bf16 v[44:47], v[170:173], v[202:205], v[44:47]
	v_mfma_f32_16x16x32_bf16 v[32:35], v[152:155], v[226:229], v[32:35]
	v_mfma_f32_16x16x32_bf16 v[28:31], v[170:173], v[226:229], v[28:31]
	v_mfma_f32_16x16x32_bf16 v[16:19], v[152:155], v[234:237], v[16:19]
	v_mfma_f32_16x16x32_bf16 v[12:15], v[170:173], v[234:237], v[12:15]
	v_mfma_f32_16x16x32_bf16 v[56:59], v[174:177], v[190:193], v[56:59]
	v_mfma_f32_16x16x32_bf16 v[52:55], v[182:185], v[190:193], v[52:55]
	v_mfma_f32_16x16x32_bf16 v[40:43], v[174:177], v[198:201], v[40:43]
	v_mfma_f32_16x16x32_bf16 v[36:39], v[182:185], v[198:201], v[36:39]
	v_mfma_f32_16x16x32_bf16 v[24:27], v[174:177], v[206:209], v[24:27]
	v_mfma_f32_16x16x32_bf16 v[20:23], v[182:185], v[206:209], v[20:23]
	v_mfma_f32_16x16x32_bf16 v[8:11], v[174:177], v[230:233], v[8:11]
	v_mfma_f32_16x16x32_bf16 v[4:7], v[182:185], v[230:233], v[4:7]
	v_mfma_f32_16x16x32_bf16 v[56:59], v[178:181], v[194:197], v[56:59]
	v_mfma_f32_16x16x32_bf16 v[52:55], v[186:189], v[194:197], v[52:55]
	v_mfma_f32_16x16x32_bf16 v[40:43], v[178:181], v[202:205], v[40:43]
	v_mfma_f32_16x16x32_bf16 v[36:39], v[186:189], v[202:205], v[36:39]
	v_mfma_f32_16x16x32_bf16 v[24:27], v[178:181], v[226:229], v[24:27]
	v_mfma_f32_16x16x32_bf16 v[20:23], v[186:189], v[226:229], v[20:23]
	v_mfma_f32_16x16x32_bf16 v[8:11], v[178:181], v[234:237], v[8:11]
	v_mfma_f32_16x16x32_bf16 v[4:7], v[186:189], v[234:237], v[4:7]
	s_setprio 0
	s_barrier
	s_add_i32 s71, s71, 2
	s_add_u32 s4, s4, 0x100
	s_addc_u32 s5, s5, 0
	s_add_u32 s61, s61, 0x100
	s_addc_u32 s70, s70, 0
	s_cmp_gt_u32 s71, 13
	s_cbranch_scc0 .LBB0_1116
	s_and_b64 vcc, exec, s[24:25]
	s_cbranch_vccz .LBB0_1119
	s_barrier

.LBB0_1578:
	s_or_b64 exec, exec, s[34:35]
	s_waitcnt vmcnt(0)
	s_and_b64 s[36:37], s[4:5], s[6:7]
	s_and_saveexec_b64 s[34:35], s[36:37]
	s_cbranch_execz .LBB0_1581
	s_mov_b64 s[36:37], exec
	v_mbcnt_lo_u32_b32 v14, s36, 0
	v_mbcnt_hi_u32_b32 v14, s37, v14
	v_cmp_eq_u32_e32 vcc, 0, v14
	s_and_b64 s[48:49], exec, vcc
	s_mov_b64 exec, s[48:49]
	s_cbranch_execz .LBB0_1581
	s_bcnt1_i32_b64 s31, s[36:37]
	v_mov_b32_e32 v14, s31
	global_atomic_add v131, v14, s[18:19]

.LBB0_1584:
	global_load_dword v15, v131, s[18:19] sc1
	v_subrev_co_u32_e32 v14, vcc, 1, v14
	s_waitcnt vmcnt(0)
	v_readfirstlane_b32 s31, v15
	s_cmpk_gt_u32 s31, 0x3f
	s_cselect_b64 s[36:37], -1, 0
	s_or_b64 s[36:37], s[36:37], vcc
	s_and_b64 vcc, exec, s[36:37]
	s_cbranch_vccz .LBB0_1583

.LBB0_1612:
	v_add_u32_e32 v160, s46, v150
	ds_read_b128 v[152:155], v160
	ds_read_b128 v[156:159], v160 offset:1024
	ds_read_b128 v[166:169], v160 offset:2048
	ds_read_b128 v[170:173], v160 offset:3072
	v_add_u32_e32 v160, s47, v150
	s_add_u32 s28, s14, s26
	ds_read_b128 v[174:177], v160
	ds_read_b128 v[178:181], v160 offset:1024
	ds_read_b128 v[182:185], v160 offset:2048
	ds_read_b128 v[186:189], v160 offset:3072
	s_addc_u32 s29, s15, s27
	s_add_u32 s28, s28, 0x100
	s_addc_u32 s29, s29, 0
	s_add_u32 s60, s49, s26
	s_addc_u32 s61, s50, s27
	s_cmpk_eq_i32 s26, 0x700
	s_cselect_b32 s31, s21, s29
	s_cselect_b32 s30, s51, s28
	s_cselect_b32 s29, s19, s61
	s_cselect_b32 s28, s58, s60
	v_lshl_add_u64 v[160:161], v[146:147], 0, s[26:27]
	s_add_i32 m0, s38, 0xc000
	ds_read_b128 v[190:193], v151
	ds_read_b128 v[194:197], v151 offset:1024
	ds_read_b128 v[198:201], v151 offset:2048
	ds_read_b128 v[202:205], v151 offset:3072
	ds_read_b128 v[206:209], v151 offset:4096
	ds_read_b128 v[226:229], v151 offset:5120
	ds_read_b128 v[230:233], v151 offset:6144
	ds_read_b128 v[234:237], v151 offset:7168
	global_load_lds_dwordx4 v[160:161], off
	v_lshl_add_u64 v[160:161], v[148:149], 0, s[26:27]
	s_add_i32 m0, s38, 0xe000
	s_nop 0
	global_load_lds_dwordx4 v[160:161], off
	s_waitcnt vmcnt(8)
	s_waitcnt lgkmcnt(0)
	s_barrier
	s_setprio 1
	s_waitcnt lgkmcnt(0)
	v_mfma_f32_16x16x32_bf16 v[122:125], v[152:155], v[190:193], v[122:125]
	v_mfma_f32_16x16x32_bf16 v[126:129], v[166:169], v[190:193], v[126:129]
	v_mfma_f32_16x16x32_bf16 v[110:113], v[152:155], v[198:201], v[110:113]
	v_mfma_f32_16x16x32_bf16 v[106:109], v[166:169], v[198:201], v[106:109]
	v_mfma_f32_16x16x32_bf16 v[94:97], v[152:155], v[206:209], v[94:97]
	v_mfma_f32_16x16x32_bf16 v[90:93], v[166:169], v[206:209], v[90:93]
	v_mfma_f32_16x16x32_bf16 v[78:81], v[152:155], v[230:233], v[78:81]
	v_mfma_f32_16x16x32_bf16 v[74:77], v[166:169], v[230:233], v[74:77]
	v_mfma_f32_16x16x32_bf16 v[122:125], v[156:159], v[194:197], v[122:125]
	v_mfma_f32_16x16x32_bf16 v[126:129], v[170:173], v[194:197], v[126:129]
	v_mfma_f32_16x16x32_bf16 v[110:113], v[156:159], v[202:205], v[110:113]
	v_mfma_f32_16x16x32_bf16 v[106:109], v[170:173], v[202:205], v[106:109]
	v_mfma_f32_16x16x32_bf16 v[94:97], v[156:159], v[226:229], v[94:97]
	v_mfma_f32_16x16x32_bf16 v[90:93], v[170:173], v[226:229], v[90:93]
	v_mfma_f32_16x16x32_bf16 v[78:81], v[156:159], v[234:237], v[78:81]
	v_mfma_f32_16x16x32_bf16 v[74:77], v[170:173], v[234:237], v[74:77]
	v_mfma_f32_16x16x32_bf16 v[118:121], v[174:177], v[190:193], v[118:121]
	v_mfma_f32_16x16x32_bf16 v[114:117], v[182:185], v[190:193], v[114:117]
	v_mfma_f32_16x16x32_bf16 v[102:105], v[174:177], v[198:201], v[102:105]
	v_mfma_f32_16x16x32_bf16 v[98:101], v[182:185], v[198:201], v[98:101]
	v_mfma_f32_16x16x32_bf16 v[86:89], v[174:177], v[206:209], v[86:89]
	v_mfma_f32_16x16x32_bf16 v[82:85], v[182:185], v[206:209], v[82:85]
	v_mfma_f32_16x16x32_bf16 v[70:73], v[174:177], v[230:233], v[70:73]
	v_mfma_f32_16x16x32_bf16 v[66:69], v[182:185], v[230:233], v[66:69]
	v_mfma_f32_16x16x32_bf16 v[118:121], v[178:181], v[194:197], v[118:121]
	v_mfma_f32_16x16x32_bf16 v[114:117], v[186:189], v[194:197], v[114:117]
	v_mfma_f32_16x16x32_bf16 v[102:105], v[178:181], v[202:205], v[102:105]
	v_mfma_f32_16x16x32_bf16 v[98:101], v[186:189], v[202:205], v[98:101]
	v_mfma_f32_16x16x32_bf16 v[86:89], v[178:181], v[226:229], v[86:89]
	v_mfma_f32_16x16x32_bf16 v[82:85], v[186:189], v[226:229], v[82:85]
	v_mfma_f32_16x16x32_bf16 v[70:73], v[178:181], v[234:237], v[70:73]
	v_mfma_f32_16x16x32_bf16 v[66:69], v[186:189], v[234:237], v[66:69]
	s_setprio 0
	s_barrier
	s_add_i32 s60, s46, s37
	v_lshl_add_u64 v[160:161], s[28:29], 0, v[132:133]
	s_mov_b32 m0, s60
	ds_read_b128 v[190:193], v151 offset:16384
	ds_read_b128 v[194:197], v151 offset:17408
	ds_read_b128 v[198:201], v151 offset:18432
	ds_read_b128 v[202:205], v151 offset:19456
	ds_read_b128 v[206:209], v151 offset:20480
	ds_read_b128 v[226:229], v151 offset:21504
	ds_read_b128 v[230:233], v151 offset:22528
	ds_read_b128 v[234:237], v151 offset:23552
	global_load_lds_dwordx4 v[160:161], off
	s_add_i32 m0, s60, 0x2000
	s_add_u32 s60, s28, 0x40000
	v_lshl_add_u64 v[210:211], s[28:29], 0, v[136:137]
	s_addc_u32 s61, s29, 0
	s_add_i32 s64, s47, s37
	global_load_lds_dwordx4 v[210:211], off
	v_lshl_add_u64 v[214:215], s[60:61], 0, v[132:133]
	s_mov_b32 m0, s64
	v_lshl_add_u64 v[220:221], s[30:31], 0, v[134:135]
	global_load_lds_dwordx4 v[214:215], off
	v_lshl_add_u64 v[214:215], s[60:61], 0, v[136:137]
	s_add_i32 m0, s64, 0x2000
	s_nop 0
	global_load_lds_dwordx4 v[214:215], off
	v_lshl_add_u64 v[214:215], s[30:31], 0, v[130:131]
	s_mov_b32 m0, s38
	s_nop 0
	global_load_lds_dwordx4 v[214:215], off
	s_mov_b32 m0, s39
	s_nop 0
	global_load_lds_dwordx4 v[220:221], off
	s_waitcnt vmcnt(8)
	s_waitcnt lgkmcnt(0)
	s_barrier
	s_setprio 1
	s_waitcnt lgkmcnt(0)
	v_mfma_f32_16x16x32_bf16 v[62:65], v[152:155], v[190:193], v[62:65]
	v_mfma_f32_16x16x32_bf16 v[58:61], v[166:169], v[190:193], v[58:61]
	v_mfma_f32_16x16x32_bf16 v[46:49], v[152:155], v[198:201], v[46:49]
	v_mfma_f32_16x16x32_bf16 v[42:45], v[166:169], v[198:201], v[42:45]
	v_mfma_f32_16x16x32_bf16 v[30:33], v[152:155], v[206:209], v[30:33]
	v_mfma_f32_16x16x32_bf16 v[26:29], v[166:169], v[206:209], v[26:29]
	v_mfma_f32_16x16x32_bf16 v[14:17], v[152:155], v[230:233], v[14:17]
	v_mfma_f32_16x16x32_bf16 v[10:13], v[166:169], v[230:233], v[10:13]
	v_mfma_f32_16x16x32_bf16 v[62:65], v[156:159], v[194:197], v[62:65]
	v_mfma_f32_16x16x32_bf16 v[58:61], v[170:173], v[194:197], v[58:61]
	v_mfma_f32_16x16x32_bf16 v[46:49], v[156:159], v[202:205], v[46:49]
	v_mfma_f32_16x16x32_bf16 v[42:45], v[170:173], v[202:205], v[42:45]
	v_mfma_f32_16x16x32_bf16 v[30:33], v[156:159], v[226:229], v[30:33]
	v_mfma_f32_16x16x32_bf16 v[26:29], v[170:173], v[226:229], v[26:29]
	v_mfma_f32_16x16x32_bf16 v[14:17], v[156:159], v[234:237], v[14:17]
	v_mfma_f32_16x16x32_bf16 v[10:13], v[170:173], v[234:237], v[10:13]
	v_mfma_f32_16x16x32_bf16 v[54:57], v[174:177], v[190:193], v[54:57]
	v_mfma_f32_16x16x32_bf16 v[50:53], v[182:185], v[190:193], v[50:53]
	v_mfma_f32_16x16x32_bf16 v[38:41], v[174:177], v[198:201], v[38:41]
	v_mfma_f32_16x16x32_bf16 v[34:37], v[182:185], v[198:201], v[34:37]
	v_mfma_f32_16x16x32_bf16 v[22:25], v[174:177], v[206:209], v[22:25]
	v_mfma_f32_16x16x32_bf16 v[18:21], v[182:185], v[206:209], v[18:21]
	v_mfma_f32_16x16x32_bf16 v[6:9], v[174:177], v[230:233], v[6:9]
	v_mfma_f32_16x16x32_bf16 v[2:5], v[182:185], v[230:233], v[2:5]
	v_mfma_f32_16x16x32_bf16 v[54:57], v[178:181], v[194:197], v[54:57]
	v_mfma_f32_16x16x32_bf16 v[50:53], v[186:189], v[194:197], v[50:53]
	v_mfma_f32_16x16x32_bf16 v[38:41], v[178:181], v[202:205], v[38:41]
	v_mfma_f32_16x16x32_bf16 v[34:37], v[186:189], v[202:205], v[34:37]
	v_mfma_f32_16x16x32_bf16 v[22:25], v[178:181], v[226:229], v[22:25]
	v_mfma_f32_16x16x32_bf16 v[18:21], v[186:189], v[226:229], v[18:21]
	v_mfma_f32_16x16x32_bf16 v[6:9], v[178:181], v[234:237], v[6:9]
	v_mfma_f32_16x16x32_bf16 v[2:5], v[186:189], v[234:237], v[2:5]
	s_setprio 0
	s_barrier
	s_add_i32 s60, 0, 0x18000
	v_add_u32_e32 v163, s60, v150
	s_add_i32 s61, 0, 0x1c000
	ds_read_b128 v[152:155], v163
	ds_read_b128 v[156:159], v163 offset:1024
	ds_read_b128 v[166:169], v163 offset:2048
	ds_read_b128 v[170:173], v163 offset:3072
	v_add_u32_e32 v163, s61, v150
	ds_read_b128 v[174:177], v163
	ds_read_b128 v[178:181], v163 offset:1024
	ds_read_b128 v[182:185], v163 offset:2048
	ds_read_b128 v[186:189], v163 offset:3072
	s_add_u32 s30, s30, 0x40000
	s_addc_u32 s31, s31, 0
	s_mov_b32 m0, s40
	v_lshl_add_u64 v[238:239], s[30:31], 0, v[130:131]
	ds_read_b128 v[190:193], v151 offset:32768
	ds_read_b128 v[194:197], v151 offset:33792
	ds_read_b128 v[198:201], v151 offset:34816
	ds_read_b128 v[202:205], v151 offset:35840
	ds_read_b128 v[206:209], v151 offset:36864
	ds_read_b128 v[226:229], v151 offset:37888
	ds_read_b128 v[230:233], v151 offset:38912
	ds_read_b128 v[234:237], v151 offset:39936
	global_load_lds_dwordx4 v[238:239], off
	v_lshl_add_u64 v[238:239], s[30:31], 0, v[134:135]
	s_mov_b32 m0, s41
	s_nop 0
	global_load_lds_dwordx4 v[238:239], off
	s_waitcnt vmcnt(8)
	s_waitcnt lgkmcnt(0)
	s_barrier
	s_setprio 1
	s_waitcnt lgkmcnt(0)
	v_mfma_f32_16x16x32_bf16 v[122:125], v[152:155], v[190:193], v[122:125]
	v_mfma_f32_16x16x32_bf16 v[126:129], v[166:169], v[190:193], v[126:129]
	v_mfma_f32_16x16x32_bf16 v[110:113], v[152:155], v[198:201], v[110:113]
	v_mfma_f32_16x16x32_bf16 v[106:109], v[166:169], v[198:201], v[106:109]
	v_mfma_f32_16x16x32_bf16 v[94:97], v[152:155], v[206:209], v[94:97]
	v_mfma_f32_16x16x32_bf16 v[90:93], v[166:169], v[206:209], v[90:93]
	v_mfma_f32_16x16x32_bf16 v[78:81], v[152:155], v[230:233], v[78:81]
	v_mfma_f32_16x16x32_bf16 v[74:77], v[166:169], v[230:233], v[74:77]
	v_mfma_f32_16x16x32_bf16 v[122:125], v[156:159], v[194:197], v[122:125]
	v_mfma_f32_16x16x32_bf16 v[126:129], v[170:173], v[194:197], v[126:129]
	v_mfma_f32_16x16x32_bf16 v[110:113], v[156:159], v[202:205], v[110:113]
	v_mfma_f32_16x16x32_bf16 v[106:109], v[170:173], v[202:205], v[106:109]
	v_mfma_f32_16x16x32_bf16 v[94:97], v[156:159], v[226:229], v[94:97]
	v_mfma_f32_16x16x32_bf16 v[90:93], v[170:173], v[226:229], v[90:93]
	v_mfma_f32_16x16x32_bf16 v[78:81], v[156:159], v[234:237], v[78:81]
	v_mfma_f32_16x16x32_bf16 v[74:77], v[170:173], v[234:237], v[74:77]
	v_mfma_f32_16x16x32_bf16 v[118:121], v[174:177], v[190:193], v[118:121]
	v_mfma_f32_16x16x32_bf16 v[114:117], v[182:185], v[190:193], v[114:117]
	v_mfma_f32_16x16x32_bf16 v[102:105], v[174:177], v[198:201], v[102:105]
	v_mfma_f32_16x16x32_bf16 v[98:101], v[182:185], v[198:201], v[98:101]
	v_mfma_f32_16x16x32_bf16 v[86:89], v[174:177], v[206:209], v[86:89]
	v_mfma_f32_16x16x32_bf16 v[82:85], v[182:185], v[206:209], v[82:85]
	v_mfma_f32_16x16x32_bf16 v[70:73], v[174:177], v[230:233], v[70:73]
	v_mfma_f32_16x16x32_bf16 v[66:69], v[182:185], v[230:233], v[66:69]
	v_mfma_f32_16x16x32_bf16 v[118:121], v[178:181], v[194:197], v[118:121]
	v_mfma_f32_16x16x32_bf16 v[114:117], v[186:189], v[194:197], v[114:117]
	v_mfma_f32_16x16x32_bf16 v[102:105], v[178:181], v[202:205], v[102:105]
	v_mfma_f32_16x16x32_bf16 v[98:101], v[186:189], v[202:205], v[98:101]
	v_mfma_f32_16x16x32_bf16 v[86:89], v[178:181], v[226:229], v[86:89]
	v_mfma_f32_16x16x32_bf16 v[82:85], v[186:189], v[226:229], v[82:85]
	v_mfma_f32_16x16x32_bf16 v[70:73], v[178:181], v[234:237], v[70:73]
	v_mfma_f32_16x16x32_bf16 v[66:69], v[186:189], v[234:237], v[66:69]
	s_setprio 0
	s_barrier
	s_add_i32 s30, s60, s37
	v_lshl_add_u64 v[160:161], v[160:161], 0, s[16:17]
	s_mov_b32 m0, s30
	ds_read_b128 v[190:193], v151 offset:49152
	ds_read_b128 v[194:197], v151 offset:50176
	ds_read_b128 v[198:201], v151 offset:51200
	ds_read_b128 v[202:205], v151 offset:52224
	ds_read_b128 v[206:209], v151 offset:53248
	ds_read_b128 v[226:229], v151 offset:54272
	ds_read_b128 v[230:233], v151 offset:55296
	ds_read_b128 v[234:237], v151 offset:56320
	global_load_lds_dwordx4 v[160:161], off
	s_add_i32 m0, s30, 0x2000
	s_add_u32 s28, s28, 0x40080
	v_lshl_add_u64 v[160:161], v[210:211], 0, s[16:17]
	s_addc_u32 s29, s29, 0
	s_add_i32 s30, s61, s37
	global_load_lds_dwordx4 v[160:161], off
	v_lshl_add_u64 v[160:161], s[28:29], 0, v[132:133]
	s_mov_b32 m0, s30
	s_nop 0
	global_load_lds_dwordx4 v[160:161], off
	v_lshl_add_u64 v[160:161], s[28:29], 0, v[136:137]
	s_add_i32 m0, s30, 0x2000
	s_nop 0
	global_load_lds_dwordx4 v[160:161], off
	v_lshl_add_u64 v[160:161], v[214:215], 0, s[16:17]
	s_mov_b32 m0, s43
	s_nop 0
	global_load_lds_dwordx4 v[160:161], off
	v_lshl_add_u64 v[160:161], v[220:221], 0, s[16:17]
	s_mov_b32 m0, s44
	s_nop 0
	global_load_lds_dwordx4 v[160:161], off
	s_waitcnt vmcnt(8)
	s_waitcnt lgkmcnt(0)
	s_barrier
	s_setprio 1
	s_waitcnt lgkmcnt(0)
	v_mfma_f32_16x16x32_bf16 v[62:65], v[152:155], v[190:193], v[62:65]
	v_mfma_f32_16x16x32_bf16 v[58:61], v[166:169], v[190:193], v[58:61]
	v_mfma_f32_16x16x32_bf16 v[46:49], v[152:155], v[198:201], v[46:49]
	v_mfma_f32_16x16x32_bf16 v[42:45], v[166:169], v[198:201], v[42:45]
	v_mfma_f32_16x16x32_bf16 v[30:33], v[152:155], v[206:209], v[30:33]
	v_mfma_f32_16x16x32_bf16 v[26:29], v[166:169], v[206:209], v[26:29]
	v_mfma_f32_16x16x32_bf16 v[14:17], v[152:155], v[230:233], v[14:17]
	v_mfma_f32_16x16x32_bf16 v[10:13], v[166:169], v[230:233], v[10:13]
	v_mfma_f32_16x16x32_bf16 v[62:65], v[156:159], v[194:197], v[62:65]
	v_mfma_f32_16x16x32_bf16 v[58:61], v[170:173], v[194:197], v[58:61]
	v_mfma_f32_16x16x32_bf16 v[46:49], v[156:159], v[202:205], v[46:49]
	v_mfma_f32_16x16x32_bf16 v[42:45], v[170:173], v[202:205], v[42:45]
	v_mfma_f32_16x16x32_bf16 v[30:33], v[156:159], v[226:229], v[30:33]
	v_mfma_f32_16x16x32_bf16 v[26:29], v[170:173], v[226:229], v[26:29]
	v_mfma_f32_16x16x32_bf16 v[14:17], v[156:159], v[234:237], v[14:17]
	v_mfma_f32_16x16x32_bf16 v[10:13], v[170:173], v[234:237], v[10:13]
	v_mfma_f32_16x16x32_bf16 v[54:57], v[174:177], v[190:193], v[54:57]
	v_mfma_f32_16x16x32_bf16 v[50:53], v[182:185], v[190:193], v[50:53]
	v_mfma_f32_16x16x32_bf16 v[38:41], v[174:177], v[198:201], v[38:41]
	v_mfma_f32_16x16x32_bf16 v[34:37], v[182:185], v[198:201], v[34:37]
	v_mfma_f32_16x16x32_bf16 v[22:25], v[174:177], v[206:209], v[22:25]
	v_mfma_f32_16x16x32_bf16 v[18:21], v[182:185], v[206:209], v[18:21]
	v_mfma_f32_16x16x32_bf16 v[6:9], v[174:177], v[230:233], v[6:9]
	v_mfma_f32_16x16x32_bf16 v[2:5], v[182:185], v[230:233], v[2:5]
	v_mfma_f32_16x16x32_bf16 v[54:57], v[178:181], v[194:197], v[54:57]
	v_mfma_f32_16x16x32_bf16 v[50:53], v[186:189], v[194:197], v[50:53]
	v_mfma_f32_16x16x32_bf16 v[38:41], v[178:181], v[202:205], v[38:41]
	v_mfma_f32_16x16x32_bf16 v[34:37], v[186:189], v[202:205], v[34:37]
	v_mfma_f32_16x16x32_bf16 v[22:25], v[178:181], v[226:229], v[22:25]
	v_mfma_f32_16x16x32_bf16 v[18:21], v[186:189], v[226:229], v[18:21]
	v_mfma_f32_16x16x32_bf16 v[6:9], v[178:181], v[234:237], v[6:9]
	v_mfma_f32_16x16x32_bf16 v[2:5], v[186:189], v[234:237], v[2:5]
	s_setprio 0
	s_barrier
	s_add_i32 s59, s59, 2
	s_add_u32 s26, s26, 0x100
	s_addc_u32 s27, s27, 0
	s_cmp_gt_u32 s59, 13
	s_cbranch_scc0 .LBB0_1612
	s_add_u32 s26, s49, 0xffffff00
	s_addc_u32 s27, s50, -1
	s_andn2_b64 vcc, exec, s[4:5]
	s_cbranch_vccnz .LBB0_1603
	v_mov_b32_e32 v2, 0
	s_mov_b32 s6, s18
	s_mov_b32 s12, s20
	s_mov_b64 s[14:15], s[24:25]
	s_mov_b32 s45, s48
	v_mov_b32_e32 v3, v2
	v_mov_b32_e32 v4, v2
	v_mov_b32_e32 v5, v2
	v_mov_b32_e32 v6, v2
	v_mov_b32_e32 v7, v2
	v_mov_b32_e32 v8, v2
	v_mov_b32_e32 v9, v2
	v_mov_b32_e32 v18, v2
	v_mov_b32_e32 v19, v2
	v_mov_b32_e32 v20, v2
	v_mov_b32_e32 v21, v2
	v_mov_b32_e32 v22, v2
	v_mov_b32_e32 v23, v2
	v_mov_b32_e32 v24, v2
	v_mov_b32_e32 v25, v2
	v_mov_b32_e32 v34, v2
	v_mov_b32_e32 v35, v2
	v_mov_b32_e32 v36, v2
	v_mov_b32_e32 v37, v2
	v_mov_b32_e32 v38, v2
	v_mov_b32_e32 v39, v2
	v_mov_b32_e32 v40, v2
	v_mov_b32_e32 v41, v2
	v_mov_b32_e32 v50, v2
	v_mov_b32_e32 v51, v2
	v_mov_b32_e32 v52, v2
	v_mov_b32_e32 v53, v2
	v_mov_b32_e32 v54, v2
	v_mov_b32_e32 v55, v2
	v_mov_b32_e32 v56, v2
	v_mov_b32_e32 v57, v2
	v_mov_b32_e32 v10, v2
	v_mov_b32_e32 v11, v2
	v_mov_b32_e32 v12, v2
	v_mov_b32_e32 v13, v2
	v_mov_b32_e32 v14, v2
	v_mov_b32_e32 v15, v2
	v_mov_b32_e32 v16, v2
	v_mov_b32_e32 v17, v2
	v_mov_b32_e32 v26, v2
	v_mov_b32_e32 v27, v2
	v_mov_b32_e32 v28, v2
	v_mov_b32_e32 v29, v2
	v_mov_b32_e32 v30, v2
	v_mov_b32_e32 v31, v2
	v_mov_b32_e32 v32, v2
	v_mov_b32_e32 v33, v2
	v_mov_b32_e32 v42, v2
	v_mov_b32_e32 v43, v2
	v_mov_b32_e32 v44, v2
	v_mov_b32_e32 v45, v2
	v_mov_b32_e32 v46, v2
	v_mov_b32_e32 v47, v2
	v_mov_b32_e32 v48, v2
	v_mov_b32_e32 v49, v2
	v_mov_b32_e32 v58, v2
	v_mov_b32_e32 v59, v2
	v_mov_b32_e32 v60, v2
	v_mov_b32_e32 v61, v2
	v_mov_b32_e32 v62, v2
	v_mov_b32_e32 v63, v2
	v_mov_b32_e32 v64, v2
	v_mov_b32_e32 v65, v2
	v_mov_b32_e32 v66, v2
	v_mov_b32_e32 v67, v2
	v_mov_b32_e32 v68, v2
	v_mov_b32_e32 v69, v2
	v_mov_b32_e32 v70, v2
	v_mov_b32_e32 v71, v2
	v_mov_b32_e32 v72, v2
	v_mov_b32_e32 v73, v2
	v_mov_b32_e32 v82, v2
	v_mov_b32_e32 v83, v2
	v_mov_b32_e32 v84, v2
	v_mov_b32_e32 v85, v2
	v_mov_b32_e32 v86, v2
	v_mov_b32_e32 v87, v2
	v_mov_b32_e32 v88, v2
	v_mov_b32_e32 v89, v2
	v_mov_b32_e32 v98, v2
	v_mov_b32_e32 v99, v2
	v_mov_b32_e32 v100, v2
	v_mov_b32_e32 v101, v2
	v_mov_b32_e32 v102, v2
	v_mov_b32_e32 v103, v2
	v_mov_b32_e32 v104, v2
	v_mov_b32_e32 v105, v2
	v_mov_b32_e32 v114, v2
	v_mov_b32_e32 v115, v2
	v_mov_b32_e32 v116, v2
	v_mov_b32_e32 v117, v2
	v_mov_b32_e32 v118, v2
	v_mov_b32_e32 v119, v2
	v_mov_b32_e32 v120, v2
	v_mov_b32_e32 v121, v2
	v_mov_b32_e32 v74, v2
	v_mov_b32_e32 v75, v2
	v_mov_b32_e32 v76, v2
	v_mov_b32_e32 v77, v2
	v_mov_b32_e32 v78, v2
	v_mov_b32_e32 v79, v2
	v_mov_b32_e32 v80, v2
	v_mov_b32_e32 v81, v2
	v_mov_b32_e32 v90, v2
	v_mov_b32_e32 v91, v2
	v_mov_b32_e32 v92, v2
	v_mov_b32_e32 v93, v2
	v_mov_b32_e32 v94, v2
	v_mov_b32_e32 v95, v2
	v_mov_b32_e32 v96, v2
	v_mov_b32_e32 v97, v2
	v_mov_b32_e32 v106, v2
	v_mov_b32_e32 v107, v2
	v_mov_b32_e32 v108, v2
	v_mov_b32_e32 v109, v2
	v_mov_b32_e32 v110, v2
	v_mov_b32_e32 v111, v2
	v_mov_b32_e32 v112, v2
	v_mov_b32_e32 v113, v2
	v_mov_b32_e32 v126, v2
	v_mov_b32_e32 v127, v2
	v_mov_b32_e32 v128, v2
	v_mov_b32_e32 v129, v2
	v_mov_b32_e32 v122, v2
	v_mov_b32_e32 v123, v2
	v_mov_b32_e32 v124, v2
	v_mov_b32_e32 v125, v2
	s_andn2_b64 vcc, exec, s[0:1]
	s_cbranch_vccnz .LBB0_1604

.LBB0_1753:
	ds_read_b128 v[146:149], v157
	ds_read_b128 v[160:163], v157 offset:1024
	ds_read_b128 v[164:167], v157 offset:2048
	ds_read_b128 v[168:171], v157 offset:3072
	ds_read_b128 v[172:175], v158
	ds_read_b128 v[176:179], v158 offset:1024
	ds_read_b128 v[180:183], v158 offset:2048
	ds_read_b128 v[184:187], v158 offset:3072
	s_add_u32 s38, s36, 0xfffc0080
	s_addc_u32 s39, s37, -1
	s_cmp_eq_u32 s65, 12
	s_cselect_b32 s41, s27, s39
	s_cselect_b32 s40, s59, s38
	s_cselect_b32 s39, s25, s64
	s_cselect_b32 s38, s60, s61
	v_lshl_add_u64 v[150:151], s[36:37], 0, v[138:139]
	s_add_i32 m0, s35, 0xc000
	ds_read_b128 v[188:191], v159
	ds_read_b128 v[192:195], v159 offset:1024
	ds_read_b128 v[196:199], v159 offset:2048
	ds_read_b128 v[200:203], v159 offset:3072
	ds_read_b128 v[204:207], v159 offset:4096
	ds_read_b128 v[208:211], v159 offset:5120
	ds_read_b128 v[218:221], v159 offset:6144
	ds_read_b128 v[226:229], v159 offset:7168
	global_load_lds_dwordx4 v[150:151], off
	v_lshl_add_u64 v[150:151], s[36:37], 0, v[140:141]
	s_add_i32 m0, s35, 0xe000
	s_nop 0
	global_load_lds_dwordx4 v[150:151], off
	s_waitcnt vmcnt(8)
	s_waitcnt lgkmcnt(0)
	s_barrier
	s_setprio 1
	s_waitcnt lgkmcnt(0)
	v_mfma_f32_16x16x32_bf16 v[126:129], v[146:149], v[188:191], v[126:129]
	v_mfma_f32_16x16x32_bf16 v[122:125], v[164:167], v[188:191], v[122:125]
	v_mfma_f32_16x16x32_bf16 v[110:113], v[146:149], v[196:199], v[110:113]
	v_mfma_f32_16x16x32_bf16 v[106:109], v[164:167], v[196:199], v[106:109]
	v_mfma_f32_16x16x32_bf16 v[94:97], v[146:149], v[204:207], v[94:97]
	v_mfma_f32_16x16x32_bf16 v[90:93], v[164:167], v[204:207], v[90:93]
	v_mfma_f32_16x16x32_bf16 v[78:81], v[146:149], v[218:221], v[78:81]
	v_mfma_f32_16x16x32_bf16 v[74:77], v[164:167], v[218:221], v[74:77]
	v_mfma_f32_16x16x32_bf16 v[126:129], v[160:163], v[192:195], v[126:129]
	v_mfma_f32_16x16x32_bf16 v[122:125], v[168:171], v[192:195], v[122:125]
	v_mfma_f32_16x16x32_bf16 v[110:113], v[160:163], v[200:203], v[110:113]
	v_mfma_f32_16x16x32_bf16 v[106:109], v[168:171], v[200:203], v[106:109]
	v_mfma_f32_16x16x32_bf16 v[94:97], v[160:163], v[208:211], v[94:97]
	v_mfma_f32_16x16x32_bf16 v[90:93], v[168:171], v[208:211], v[90:93]
	v_mfma_f32_16x16x32_bf16 v[78:81], v[160:163], v[226:229], v[78:81]
	v_mfma_f32_16x16x32_bf16 v[74:77], v[168:171], v[226:229], v[74:77]
	v_mfma_f32_16x16x32_bf16 v[118:121], v[172:175], v[188:191], v[118:121]
	v_mfma_f32_16x16x32_bf16 v[114:117], v[180:183], v[188:191], v[114:117]
	v_mfma_f32_16x16x32_bf16 v[102:105], v[172:175], v[196:199], v[102:105]
	v_mfma_f32_16x16x32_bf16 v[98:101], v[180:183], v[196:199], v[98:101]
	v_mfma_f32_16x16x32_bf16 v[86:89], v[172:175], v[204:207], v[86:89]
	v_mfma_f32_16x16x32_bf16 v[82:85], v[180:183], v[204:207], v[82:85]
	v_mfma_f32_16x16x32_bf16 v[70:73], v[172:175], v[218:221], v[70:73]
	v_mfma_f32_16x16x32_bf16 v[66:69], v[180:183], v[218:221], v[66:69]
	v_mfma_f32_16x16x32_bf16 v[118:121], v[176:179], v[192:195], v[118:121]
	v_mfma_f32_16x16x32_bf16 v[114:117], v[184:187], v[192:195], v[114:117]
	v_mfma_f32_16x16x32_bf16 v[102:105], v[176:179], v[200:203], v[102:105]
	v_mfma_f32_16x16x32_bf16 v[98:101], v[184:187], v[200:203], v[98:101]
	v_mfma_f32_16x16x32_bf16 v[86:89], v[176:179], v[208:211], v[86:89]
	v_mfma_f32_16x16x32_bf16 v[82:85], v[184:187], v[208:211], v[82:85]
	v_mfma_f32_16x16x32_bf16 v[70:73], v[176:179], v[226:229], v[70:73]
	v_mfma_f32_16x16x32_bf16 v[66:69], v[184:187], v[226:229], v[66:69]
	s_setprio 0
	s_barrier
	s_add_i32 s66, s50, s33
	v_lshl_add_u64 v[150:151], s[38:39], 0, v[132:133]
	s_mov_b32 m0, s66
	ds_read_b128 v[188:191], v159 offset:16384
	ds_read_b128 v[192:195], v159 offset:17408
	ds_read_b128 v[196:199], v159 offset:18432
	ds_read_b128 v[200:203], v159 offset:19456
	ds_read_b128 v[204:207], v159 offset:20480
	ds_read_b128 v[208:211], v159 offset:21504
	ds_read_b128 v[218:221], v159 offset:22528
	ds_read_b128 v[226:229], v159 offset:23552
	global_load_lds_dwordx4 v[150:151], off
	s_add_i32 m0, s66, 0x2000
	s_add_u32 s66, s38, 0x40000
	v_lshl_add_u64 v[214:215], s[38:39], 0, v[136:137]
	s_addc_u32 s67, s39, 0
	s_add_i32 s68, s51, s33
	global_load_lds_dwordx4 v[214:215], off
	v_lshl_add_u64 v[230:231], s[66:67], 0, v[132:133]
	s_mov_b32 m0, s68
	v_lshl_add_u64 v[232:233], s[40:41], 0, v[134:135]
	global_load_lds_dwordx4 v[230:231], off
	v_lshl_add_u64 v[230:231], s[66:67], 0, v[136:137]
	s_add_i32 m0, s68, 0x2000
	s_nop 0
	global_load_lds_dwordx4 v[230:231], off
	v_lshl_add_u64 v[230:231], s[40:41], 0, v[130:131]
	s_mov_b32 m0, s35
	s_nop 0
	global_load_lds_dwordx4 v[230:231], off
	s_mov_b32 m0, s42
	s_nop 0
	global_load_lds_dwordx4 v[232:233], off
	s_waitcnt vmcnt(8)
	s_waitcnt lgkmcnt(0)
	s_barrier
	s_setprio 1
	s_waitcnt lgkmcnt(0)
	v_mfma_f32_16x16x32_bf16 v[62:65], v[146:149], v[188:191], v[62:65]
	v_mfma_f32_16x16x32_bf16 v[58:61], v[164:167], v[188:191], v[58:61]
	v_mfma_f32_16x16x32_bf16 v[46:49], v[146:149], v[196:199], v[46:49]
	v_mfma_f32_16x16x32_bf16 v[42:45], v[164:167], v[196:199], v[42:45]
	v_mfma_f32_16x16x32_bf16 v[30:33], v[146:149], v[204:207], v[30:33]
	v_mfma_f32_16x16x32_bf16 v[26:29], v[164:167], v[204:207], v[26:29]
	v_mfma_f32_16x16x32_bf16 v[14:17], v[146:149], v[218:221], v[14:17]
	v_mfma_f32_16x16x32_bf16 v[10:13], v[164:167], v[218:221], v[10:13]
	v_mfma_f32_16x16x32_bf16 v[62:65], v[160:163], v[192:195], v[62:65]
	v_mfma_f32_16x16x32_bf16 v[58:61], v[168:171], v[192:195], v[58:61]
	v_mfma_f32_16x16x32_bf16 v[46:49], v[160:163], v[200:203], v[46:49]
	v_mfma_f32_16x16x32_bf16 v[42:45], v[168:171], v[200:203], v[42:45]
	v_mfma_f32_16x16x32_bf16 v[30:33], v[160:163], v[208:211], v[30:33]
	v_mfma_f32_16x16x32_bf16 v[26:29], v[168:171], v[208:211], v[26:29]
	v_mfma_f32_16x16x32_bf16 v[14:17], v[160:163], v[226:229], v[14:17]
	v_mfma_f32_16x16x32_bf16 v[10:13], v[168:171], v[226:229], v[10:13]
	v_mfma_f32_16x16x32_bf16 v[54:57], v[172:175], v[188:191], v[54:57]
	v_mfma_f32_16x16x32_bf16 v[50:53], v[180:183], v[188:191], v[50:53]
	v_mfma_f32_16x16x32_bf16 v[38:41], v[172:175], v[196:199], v[38:41]
	v_mfma_f32_16x16x32_bf16 v[34:37], v[180:183], v[196:199], v[34:37]
	v_mfma_f32_16x16x32_bf16 v[22:25], v[172:175], v[204:207], v[22:25]
	v_mfma_f32_16x16x32_bf16 v[18:21], v[180:183], v[204:207], v[18:21]
	v_mfma_f32_16x16x32_bf16 v[6:9], v[172:175], v[218:221], v[6:9]
	v_mfma_f32_16x16x32_bf16 v[2:5], v[180:183], v[218:221], v[2:5]
	v_mfma_f32_16x16x32_bf16 v[54:57], v[176:179], v[192:195], v[54:57]
	v_mfma_f32_16x16x32_bf16 v[50:53], v[184:187], v[192:195], v[50:53]
	v_mfma_f32_16x16x32_bf16 v[38:41], v[176:179], v[200:203], v[38:41]
	v_mfma_f32_16x16x32_bf16 v[34:37], v[184:187], v[200:203], v[34:37]
	v_mfma_f32_16x16x32_bf16 v[22:25], v[176:179], v[208:211], v[22:25]
	v_mfma_f32_16x16x32_bf16 v[18:21], v[184:187], v[208:211], v[18:21]
	v_mfma_f32_16x16x32_bf16 v[6:9], v[176:179], v[226:229], v[6:9]
	v_mfma_f32_16x16x32_bf16 v[2:5], v[184:187], v[226:229], v[2:5]
	s_setprio 0
	s_barrier
	s_add_i32 s66, 0, 0x18000
	s_add_i32 s67, 0, 0x1c000
	v_add_u32_e32 v168, s66, v153
	v_add_u32_e32 v184, s67, v153
	ds_read_b128 v[146:149], v168
	ds_read_b128 v[160:163], v168 offset:1024
	ds_read_b128 v[164:167], v168 offset:2048
	ds_read_b128 v[168:171], v168 offset:3072
	ds_read_b128 v[172:175], v184
	ds_read_b128 v[176:179], v184 offset:1024
	ds_read_b128 v[180:183], v184 offset:2048
	ds_read_b128 v[184:187], v184 offset:3072
	s_add_u32 s40, s40, 0x40000
	s_addc_u32 s41, s41, 0
	s_mov_b32 m0, s43
	v_lshl_add_u64 v[234:235], s[40:41], 0, v[130:131]
	ds_read_b128 v[188:191], v159 offset:32768
	ds_read_b128 v[192:195], v159 offset:33792
	ds_read_b128 v[196:199], v159 offset:34816
	ds_read_b128 v[200:203], v159 offset:35840
	ds_read_b128 v[204:207], v159 offset:36864
	ds_read_b128 v[208:211], v159 offset:37888
	ds_read_b128 v[218:221], v159 offset:38912
	ds_read_b128 v[226:229], v159 offset:39936
	global_load_lds_dwordx4 v[234:235], off
	v_lshl_add_u64 v[234:235], s[40:41], 0, v[134:135]
	s_mov_b32 m0, s44
	s_nop 0
	global_load_lds_dwordx4 v[234:235], off
	s_waitcnt vmcnt(8)
	s_waitcnt lgkmcnt(0)
	s_barrier
	s_setprio 1
	s_waitcnt lgkmcnt(0)
	v_mfma_f32_16x16x32_bf16 v[126:129], v[146:149], v[188:191], v[126:129]
	v_mfma_f32_16x16x32_bf16 v[122:125], v[164:167], v[188:191], v[122:125]
	v_mfma_f32_16x16x32_bf16 v[110:113], v[146:149], v[196:199], v[110:113]
	v_mfma_f32_16x16x32_bf16 v[106:109], v[164:167], v[196:199], v[106:109]
	v_mfma_f32_16x16x32_bf16 v[94:97], v[146:149], v[204:207], v[94:97]
	v_mfma_f32_16x16x32_bf16 v[90:93], v[164:167], v[204:207], v[90:93]
	v_mfma_f32_16x16x32_bf16 v[78:81], v[146:149], v[218:221], v[78:81]
	v_mfma_f32_16x16x32_bf16 v[74:77], v[164:167], v[218:221], v[74:77]
	v_mfma_f32_16x16x32_bf16 v[126:129], v[160:163], v[192:195], v[126:129]
	v_mfma_f32_16x16x32_bf16 v[122:125], v[168:171], v[192:195], v[122:125]
	v_mfma_f32_16x16x32_bf16 v[110:113], v[160:163], v[200:203], v[110:113]
	v_mfma_f32_16x16x32_bf16 v[106:109], v[168:171], v[200:203], v[106:109]
	v_mfma_f32_16x16x32_bf16 v[94:97], v[160:163], v[208:211], v[94:97]
	v_mfma_f32_16x16x32_bf16 v[90:93], v[168:171], v[208:211], v[90:93]
	v_mfma_f32_16x16x32_bf16 v[78:81], v[160:163], v[226:229], v[78:81]
	v_mfma_f32_16x16x32_bf16 v[74:77], v[168:171], v[226:229], v[74:77]
	v_mfma_f32_16x16x32_bf16 v[118:121], v[172:175], v[188:191], v[118:121]
	v_mfma_f32_16x16x32_bf16 v[114:117], v[180:183], v[188:191], v[114:117]
	v_mfma_f32_16x16x32_bf16 v[102:105], v[172:175], v[196:199], v[102:105]
	v_mfma_f32_16x16x32_bf16 v[98:101], v[180:183], v[196:199], v[98:101]
	v_mfma_f32_16x16x32_bf16 v[86:89], v[172:175], v[204:207], v[86:89]
	v_mfma_f32_16x16x32_bf16 v[82:85], v[180:183], v[204:207], v[82:85]
	v_mfma_f32_16x16x32_bf16 v[70:73], v[172:175], v[218:221], v[70:73]
	v_mfma_f32_16x16x32_bf16 v[66:69], v[180:183], v[218:221], v[66:69]
	v_mfma_f32_16x16x32_bf16 v[118:121], v[176:179], v[192:195], v[118:121]
	v_mfma_f32_16x16x32_bf16 v[114:117], v[184:187], v[192:195], v[114:117]
	v_mfma_f32_16x16x32_bf16 v[102:105], v[176:179], v[200:203], v[102:105]
	v_mfma_f32_16x16x32_bf16 v[98:101], v[184:187], v[200:203], v[98:101]
	v_mfma_f32_16x16x32_bf16 v[86:89], v[176:179], v[208:211], v[86:89]
	v_mfma_f32_16x16x32_bf16 v[82:85], v[184:187], v[208:211], v[82:85]
	v_mfma_f32_16x16x32_bf16 v[70:73], v[176:179], v[226:229], v[70:73]
	v_mfma_f32_16x16x32_bf16 v[66:69], v[184:187], v[226:229], v[66:69]
	s_setprio 0
	s_barrier
	s_add_i32 s40, s66, s33
	v_lshl_add_u64 v[150:151], v[150:151], 0, s[12:13]
	s_mov_b32 m0, s40
	ds_read_b128 v[188:191], v159 offset:49152
	ds_read_b128 v[192:195], v159 offset:50176
	ds_read_b128 v[196:199], v159 offset:51200
	ds_read_b128 v[200:203], v159 offset:52224
	ds_read_b128 v[204:207], v159 offset:53248
	ds_read_b128 v[208:211], v159 offset:54272
	ds_read_b128 v[218:221], v159 offset:55296
	ds_read_b128 v[226:229], v159 offset:56320
	global_load_lds_dwordx4 v[150:151], off
	s_add_i32 m0, s40, 0x2000
	s_add_u32 s38, s38, 0x40080
	v_lshl_add_u64 v[150:151], v[214:215], 0, s[12:13]
	s_addc_u32 s39, s39, 0
	s_add_i32 s40, s67, s33
	global_load_lds_dwordx4 v[150:151], off
	v_lshl_add_u64 v[150:151], s[38:39], 0, v[132:133]
	s_mov_b32 m0, s40
	s_nop 0
	global_load_lds_dwordx4 v[150:151], off
	v_lshl_add_u64 v[150:151], s[38:39], 0, v[136:137]
	s_add_i32 m0, s40, 0x2000
	s_nop 0
	global_load_lds_dwordx4 v[150:151], off
	v_lshl_add_u64 v[150:151], v[230:231], 0, s[12:13]
	s_mov_b32 m0, s46
	s_nop 0
	global_load_lds_dwordx4 v[150:151], off
	v_lshl_add_u64 v[150:151], v[232:233], 0, s[12:13]
	s_mov_b32 m0, s47
	s_nop 0
	global_load_lds_dwordx4 v[150:151], off
	s_waitcnt vmcnt(8)
	s_waitcnt lgkmcnt(0)
	s_barrier
	s_setprio 1
	s_waitcnt lgkmcnt(0)
	v_mfma_f32_16x16x32_bf16 v[62:65], v[146:149], v[188:191], v[62:65]
	v_mfma_f32_16x16x32_bf16 v[58:61], v[164:167], v[188:191], v[58:61]
	v_mfma_f32_16x16x32_bf16 v[46:49], v[146:149], v[196:199], v[46:49]
	v_mfma_f32_16x16x32_bf16 v[42:45], v[164:167], v[196:199], v[42:45]
	v_mfma_f32_16x16x32_bf16 v[30:33], v[146:149], v[204:207], v[30:33]
	v_mfma_f32_16x16x32_bf16 v[26:29], v[164:167], v[204:207], v[26:29]
	v_mfma_f32_16x16x32_bf16 v[14:17], v[146:149], v[218:221], v[14:17]
	v_mfma_f32_16x16x32_bf16 v[10:13], v[164:167], v[218:221], v[10:13]
	v_mfma_f32_16x16x32_bf16 v[62:65], v[160:163], v[192:195], v[62:65]
	v_mfma_f32_16x16x32_bf16 v[58:61], v[168:171], v[192:195], v[58:61]
	v_mfma_f32_16x16x32_bf16 v[46:49], v[160:163], v[200:203], v[46:49]
	v_mfma_f32_16x16x32_bf16 v[42:45], v[168:171], v[200:203], v[42:45]
	v_mfma_f32_16x16x32_bf16 v[30:33], v[160:163], v[208:211], v[30:33]
	v_mfma_f32_16x16x32_bf16 v[26:29], v[168:171], v[208:211], v[26:29]
	v_mfma_f32_16x16x32_bf16 v[14:17], v[160:163], v[226:229], v[14:17]
	v_mfma_f32_16x16x32_bf16 v[10:13], v[168:171], v[226:229], v[10:13]
	v_mfma_f32_16x16x32_bf16 v[54:57], v[172:175], v[188:191], v[54:57]
	v_mfma_f32_16x16x32_bf16 v[50:53], v[180:183], v[188:191], v[50:53]
	v_mfma_f32_16x16x32_bf16 v[38:41], v[172:175], v[196:199], v[38:41]
	v_mfma_f32_16x16x32_bf16 v[34:37], v[180:183], v[196:199], v[34:37]
	v_mfma_f32_16x16x32_bf16 v[22:25], v[172:175], v[204:207], v[22:25]
	v_mfma_f32_16x16x32_bf16 v[18:21], v[180:183], v[204:207], v[18:21]
	v_mfma_f32_16x16x32_bf16 v[6:9], v[172:175], v[218:221], v[6:9]
	v_mfma_f32_16x16x32_bf16 v[2:5], v[180:183], v[218:221], v[2:5]
	v_mfma_f32_16x16x32_bf16 v[54:57], v[176:179], v[192:195], v[54:57]
	v_mfma_f32_16x16x32_bf16 v[50:53], v[184:187], v[192:195], v[50:53]
	v_mfma_f32_16x16x32_bf16 v[38:41], v[176:179], v[200:203], v[38:41]
	v_mfma_f32_16x16x32_bf16 v[34:37], v[184:187], v[200:203], v[34:37]
	v_mfma_f32_16x16x32_bf16 v[22:25], v[176:179], v[208:211], v[22:25]
	v_mfma_f32_16x16x32_bf16 v[18:21], v[184:187], v[208:211], v[18:21]
	v_mfma_f32_16x16x32_bf16 v[6:9], v[176:179], v[226:229], v[6:9]
	v_mfma_f32_16x16x32_bf16 v[2:5], v[184:187], v[226:229], v[2:5]
	s_setprio 0
	s_barrier
	s_add_i32 s65, s65, 2
	s_add_u32 s36, s36, 0x100
	s_addc_u32 s37, s37, 0
	s_add_u32 s61, s61, 0x100
	s_addc_u32 s64, s64, 0
	s_cmp_gt_u32 s65, 13
	s_cbranch_scc0 .LBB0_1753
	s_and_b64 vcc, exec, s[14:15]
	s_cbranch_vccz .LBB0_1756
	s_barrier

.LBB0_1831:
	s_or_b64 exec, exec, s[30:31]
	s_waitcnt vmcnt(0)
	s_and_b64 s[34:35], s[4:5], s[6:7]
	s_and_saveexec_b64 s[30:31], s[34:35]
	s_cbranch_execz .LBB0_1834
	s_mov_b64 s[34:35], exec
	v_mbcnt_lo_u32_b32 v13, s34, 0
	v_mbcnt_hi_u32_b32 v13, s35, v13
	v_cmp_eq_u32_e32 vcc, 0, v13
	s_and_b64 s[46:47], exec, vcc
	s_mov_b64 exec, s[46:47]
	s_cbranch_execz .LBB0_1834
	s_bcnt1_i32_b64 s29, s[34:35]
	v_mov_b32_e32 v13, s29
	global_atomic_add v133, v13, s[16:17]

.LBB0_1837:
	global_load_dword v14, v133, s[16:17] sc1
	v_subrev_co_u32_e32 v13, vcc, 1, v13
	s_waitcnt vmcnt(0)
	v_readfirstlane_b32 s29, v14
	s_cmpk_gt_u32 s29, 0x3f
	s_cselect_b64 s[34:35], -1, 0
	s_or_b64 s[34:35], s[34:35], vcc
	s_and_b64 vcc, exec, s[34:35]
	s_cbranch_vccz .LBB0_1836

.LBB0_1864:
	v_add_u32_e32 v131, s47, v151
	ds_read_b128 v[154:157], v131
	ds_read_b128 v[158:161], v131 offset:1024
	ds_read_b128 v[162:165], v131 offset:2048
	ds_read_b128 v[166:169], v131 offset:3072
	v_add_u32_e32 v131, s48, v151
	ds_read_b128 v[170:173], v131
	ds_read_b128 v[174:177], v131 offset:1024
	ds_read_b128 v[178:181], v131 offset:2048
	ds_read_b128 v[182:185], v131 offset:3072
	s_add_i32 s55, s28, 2
	s_add_u32 s58, s26, 0x80
	s_addc_u32 s29, s27, 0
	s_cmp_eq_u32 s46, s28
	s_cselect_b32 s28, s6, s58
	s_cselect_b32 s29, s7, s29
	s_cselect_b32 s59, s25, s54
	s_cselect_b32 s58, s24, s53
	v_lshl_add_u64 v[132:133], s[26:27], 0, v[142:143]
	s_add_i32 m0, s38, 0xc000
	ds_read_b128 v[186:189], v152
	ds_read_b128 v[194:197], v152 offset:1024
	ds_read_b128 v[198:201], v152 offset:2048
	ds_read_b128 v[202:205], v152 offset:3072
	ds_read_b128 v[206:209], v152 offset:4096
	ds_read_b128 v[218:221], v152 offset:5120
	ds_read_b128 v[226:229], v152 offset:6144
	ds_read_b128 v[230:233], v152 offset:7168
	global_load_lds_dwordx4 v[132:133], off
	v_lshl_add_u64 v[132:133], s[26:27], 0, v[144:145]
	s_add_i32 m0, s38, 0xe000
	s_nop 0
	global_load_lds_dwordx4 v[132:133], off
	s_waitcnt vmcnt(8)
	s_waitcnt lgkmcnt(0)
	s_barrier
	s_setprio 1
	s_waitcnt lgkmcnt(0)
	v_mfma_f32_16x16x32_bf16 v[122:125], v[154:157], v[186:189], v[122:125]
	v_mfma_f32_16x16x32_bf16 v[126:129], v[162:165], v[186:189], v[126:129]
	v_mfma_f32_16x16x32_bf16 v[114:117], v[154:157], v[198:201], v[114:117]
	v_mfma_f32_16x16x32_bf16 v[118:121], v[162:165], v[198:201], v[118:121]
	v_mfma_f32_16x16x32_bf16 v[94:97], v[154:157], v[206:209], v[94:97]
	v_mfma_f32_16x16x32_bf16 v[90:93], v[162:165], v[206:209], v[90:93]
	v_mfma_f32_16x16x32_bf16 v[78:81], v[154:157], v[226:229], v[78:81]
	v_mfma_f32_16x16x32_bf16 v[74:77], v[162:165], v[226:229], v[74:77]
	v_mfma_f32_16x16x32_bf16 v[122:125], v[158:161], v[194:197], v[122:125]
	v_mfma_f32_16x16x32_bf16 v[126:129], v[166:169], v[194:197], v[126:129]
	v_mfma_f32_16x16x32_bf16 v[114:117], v[158:161], v[202:205], v[114:117]
	v_mfma_f32_16x16x32_bf16 v[118:121], v[166:169], v[202:205], v[118:121]
	v_mfma_f32_16x16x32_bf16 v[94:97], v[158:161], v[218:221], v[94:97]
	v_mfma_f32_16x16x32_bf16 v[90:93], v[166:169], v[218:221], v[90:93]
	v_mfma_f32_16x16x32_bf16 v[78:81], v[158:161], v[230:233], v[78:81]
	v_mfma_f32_16x16x32_bf16 v[74:77], v[166:169], v[230:233], v[74:77]
	v_mfma_f32_16x16x32_bf16 v[110:113], v[170:173], v[186:189], v[110:113]
	v_mfma_f32_16x16x32_bf16 v[106:109], v[178:181], v[186:189], v[106:109]
	v_mfma_f32_16x16x32_bf16 v[102:105], v[170:173], v[198:201], v[102:105]
	v_mfma_f32_16x16x32_bf16 v[98:101], v[178:181], v[198:201], v[98:101]
	v_mfma_f32_16x16x32_bf16 v[86:89], v[170:173], v[206:209], v[86:89]
	v_mfma_f32_16x16x32_bf16 v[82:85], v[178:181], v[206:209], v[82:85]
	v_mfma_f32_16x16x32_bf16 v[70:73], v[170:173], v[226:229], v[70:73]
	v_mfma_f32_16x16x32_bf16 v[66:69], v[178:181], v[226:229], v[66:69]
	v_mfma_f32_16x16x32_bf16 v[110:113], v[174:177], v[194:197], v[110:113]
	v_mfma_f32_16x16x32_bf16 v[106:109], v[182:185], v[194:197], v[106:109]
	v_mfma_f32_16x16x32_bf16 v[102:105], v[174:177], v[202:205], v[102:105]
	v_mfma_f32_16x16x32_bf16 v[98:101], v[182:185], v[202:205], v[98:101]
	v_mfma_f32_16x16x32_bf16 v[86:89], v[174:177], v[218:221], v[86:89]
	v_mfma_f32_16x16x32_bf16 v[82:85], v[182:185], v[218:221], v[82:85]
	v_mfma_f32_16x16x32_bf16 v[70:73], v[174:177], v[230:233], v[70:73]
	v_mfma_f32_16x16x32_bf16 v[66:69], v[182:185], v[230:233], v[66:69]
	s_setprio 0
	s_barrier
	s_add_i32 s60, s47, s34
	v_lshl_add_u64 v[132:133], s[58:59], 0, v[136:137]
	s_mov_b32 m0, s60
	ds_read_b128 v[186:189], v152 offset:16384
	ds_read_b128 v[194:197], v152 offset:17408
	ds_read_b128 v[198:201], v152 offset:18432
	ds_read_b128 v[202:205], v152 offset:19456
	ds_read_b128 v[206:209], v152 offset:20480
	ds_read_b128 v[218:221], v152 offset:21504
	ds_read_b128 v[226:229], v152 offset:22528
	ds_read_b128 v[230:233], v152 offset:23552
	global_load_lds_dwordx4 v[132:133], off
	s_add_i32 m0, s60, 0x2000
	v_lshl_add_u64 v[190:191], s[58:59], 0, v[140:141]
	s_add_u32 s58, s58, s12
	s_addc_u32 s59, s59, s13
	s_add_i32 s60, s48, s34
	global_load_lds_dwordx4 v[190:191], off
	v_lshl_add_u64 v[210:211], s[58:59], 0, v[136:137]
	s_mov_b32 m0, s60
	v_lshl_add_u64 v[234:235], s[58:59], 0, v[140:141]
	global_load_lds_dwordx4 v[210:211], off
	s_add_i32 m0, s60, 0x2000
	v_lshl_add_u64 v[236:237], s[28:29], 0, v[134:135]
	global_load_lds_dwordx4 v[234:235], off
	s_mov_b32 m0, s38
	v_lshl_add_u64 v[238:239], s[28:29], 0, v[138:139]
	global_load_lds_dwordx4 v[236:237], off
	s_mov_b32 m0, s39
	s_nop 0
	global_load_lds_dwordx4 v[238:239], off
	s_waitcnt vmcnt(8)
	s_waitcnt lgkmcnt(0)
	s_barrier
	s_setprio 1
	s_waitcnt lgkmcnt(0)
	v_mfma_f32_16x16x32_bf16 v[62:65], v[154:157], v[186:189], v[62:65]
	v_mfma_f32_16x16x32_bf16 v[58:61], v[162:165], v[186:189], v[58:61]
	v_mfma_f32_16x16x32_bf16 v[46:49], v[154:157], v[198:201], v[46:49]
	v_mfma_f32_16x16x32_bf16 v[42:45], v[162:165], v[198:201], v[42:45]
	v_mfma_f32_16x16x32_bf16 v[30:33], v[154:157], v[206:209], v[30:33]
	v_mfma_f32_16x16x32_bf16 v[26:29], v[162:165], v[206:209], v[26:29]
	v_mfma_f32_16x16x32_bf16 v[14:17], v[154:157], v[226:229], v[14:17]
	v_mfma_f32_16x16x32_bf16 v[10:13], v[162:165], v[226:229], v[10:13]
	v_mfma_f32_16x16x32_bf16 v[62:65], v[158:161], v[194:197], v[62:65]
	v_mfma_f32_16x16x32_bf16 v[58:61], v[166:169], v[194:197], v[58:61]
	v_mfma_f32_16x16x32_bf16 v[46:49], v[158:161], v[202:205], v[46:49]
	v_mfma_f32_16x16x32_bf16 v[42:45], v[166:169], v[202:205], v[42:45]
	v_mfma_f32_16x16x32_bf16 v[30:33], v[158:161], v[218:221], v[30:33]
	v_mfma_f32_16x16x32_bf16 v[26:29], v[166:169], v[218:221], v[26:29]
	v_mfma_f32_16x16x32_bf16 v[14:17], v[158:161], v[230:233], v[14:17]
	v_mfma_f32_16x16x32_bf16 v[10:13], v[166:169], v[230:233], v[10:13]
	v_mfma_f32_16x16x32_bf16 v[54:57], v[170:173], v[186:189], v[54:57]
	v_mfma_f32_16x16x32_bf16 v[50:53], v[178:181], v[186:189], v[50:53]
	v_mfma_f32_16x16x32_bf16 v[38:41], v[170:173], v[198:201], v[38:41]
	v_mfma_f32_16x16x32_bf16 v[34:37], v[178:181], v[198:201], v[34:37]
	v_mfma_f32_16x16x32_bf16 v[22:25], v[170:173], v[206:209], v[22:25]
	v_mfma_f32_16x16x32_bf16 v[18:21], v[178:181], v[206:209], v[18:21]
	v_mfma_f32_16x16x32_bf16 v[6:9], v[170:173], v[226:229], v[6:9]
	v_mfma_f32_16x16x32_bf16 v[2:5], v[178:181], v[226:229], v[2:5]
	v_mfma_f32_16x16x32_bf16 v[54:57], v[174:177], v[194:197], v[54:57]
	v_mfma_f32_16x16x32_bf16 v[50:53], v[182:185], v[194:197], v[50:53]
	v_mfma_f32_16x16x32_bf16 v[38:41], v[174:177], v[202:205], v[38:41]
	v_mfma_f32_16x16x32_bf16 v[34:37], v[182:185], v[202:205], v[34:37]
	v_mfma_f32_16x16x32_bf16 v[22:25], v[174:177], v[218:221], v[22:25]
	v_mfma_f32_16x16x32_bf16 v[18:21], v[182:185], v[218:221], v[18:21]
	v_mfma_f32_16x16x32_bf16 v[6:9], v[174:177], v[230:233], v[6:9]
	v_mfma_f32_16x16x32_bf16 v[2:5], v[182:185], v[230:233], v[2:5]
	s_setprio 0
	s_barrier
	s_add_i32 s58, 0, 0x18000
	v_add_u32_e32 v131, s58, v151
	s_add_i32 s59, 0, 0x1c000
	ds_read_b128 v[154:157], v131
	ds_read_b128 v[158:161], v131 offset:1024
	ds_read_b128 v[162:165], v131 offset:2048
	ds_read_b128 v[166:169], v131 offset:3072
	v_add_u32_e32 v131, s59, v151
	ds_read_b128 v[170:173], v131
	ds_read_b128 v[174:177], v131 offset:1024
	ds_read_b128 v[178:181], v131 offset:2048
	ds_read_b128 v[182:185], v131 offset:3072
	s_add_u32 s28, s28, s12
	s_addc_u32 s29, s29, s13
	s_mov_b32 m0, s40
	v_lshl_add_u64 v[240:241], s[28:29], 0, v[134:135]
	ds_read_b128 v[186:189], v152 offset:32768
	ds_read_b128 v[194:197], v152 offset:33792
	ds_read_b128 v[198:201], v152 offset:34816
	ds_read_b128 v[202:205], v152 offset:35840
	ds_read_b128 v[206:209], v152 offset:36864
	ds_read_b128 v[218:221], v152 offset:37888
	ds_read_b128 v[226:229], v152 offset:38912
	ds_read_b128 v[230:233], v152 offset:39936
	global_load_lds_dwordx4 v[240:241], off
	v_lshl_add_u64 v[240:241], s[28:29], 0, v[138:139]
	s_mov_b32 m0, s41
	s_nop 0
	global_load_lds_dwordx4 v[240:241], off
	s_waitcnt vmcnt(8)
	s_waitcnt lgkmcnt(0)
	s_barrier
	s_setprio 1
	s_waitcnt lgkmcnt(0)
	v_mfma_f32_16x16x32_bf16 v[122:125], v[154:157], v[186:189], v[122:125]
	v_mfma_f32_16x16x32_bf16 v[126:129], v[162:165], v[186:189], v[126:129]
	v_mfma_f32_16x16x32_bf16 v[114:117], v[154:157], v[198:201], v[114:117]
	v_mfma_f32_16x16x32_bf16 v[118:121], v[162:165], v[198:201], v[118:121]
	v_mfma_f32_16x16x32_bf16 v[94:97], v[154:157], v[206:209], v[94:97]
	v_mfma_f32_16x16x32_bf16 v[90:93], v[162:165], v[206:209], v[90:93]
	v_mfma_f32_16x16x32_bf16 v[78:81], v[154:157], v[226:229], v[78:81]
	v_mfma_f32_16x16x32_bf16 v[74:77], v[162:165], v[226:229], v[74:77]
	v_mfma_f32_16x16x32_bf16 v[122:125], v[158:161], v[194:197], v[122:125]
	v_mfma_f32_16x16x32_bf16 v[126:129], v[166:169], v[194:197], v[126:129]
	v_mfma_f32_16x16x32_bf16 v[114:117], v[158:161], v[202:205], v[114:117]
	v_mfma_f32_16x16x32_bf16 v[118:121], v[166:169], v[202:205], v[118:121]
	v_mfma_f32_16x16x32_bf16 v[94:97], v[158:161], v[218:221], v[94:97]
	v_mfma_f32_16x16x32_bf16 v[90:93], v[166:169], v[218:221], v[90:93]
	v_mfma_f32_16x16x32_bf16 v[78:81], v[158:161], v[230:233], v[78:81]
	v_mfma_f32_16x16x32_bf16 v[74:77], v[166:169], v[230:233], v[74:77]
	v_mfma_f32_16x16x32_bf16 v[110:113], v[170:173], v[186:189], v[110:113]
	v_mfma_f32_16x16x32_bf16 v[106:109], v[178:181], v[186:189], v[106:109]
	v_mfma_f32_16x16x32_bf16 v[102:105], v[170:173], v[198:201], v[102:105]
	v_mfma_f32_16x16x32_bf16 v[98:101], v[178:181], v[198:201], v[98:101]
	v_mfma_f32_16x16x32_bf16 v[86:89], v[170:173], v[206:209], v[86:89]
	v_mfma_f32_16x16x32_bf16 v[82:85], v[178:181], v[206:209], v[82:85]
	v_mfma_f32_16x16x32_bf16 v[70:73], v[170:173], v[226:229], v[70:73]
	v_mfma_f32_16x16x32_bf16 v[66:69], v[178:181], v[226:229], v[66:69]
	v_mfma_f32_16x16x32_bf16 v[110:113], v[174:177], v[194:197], v[110:113]
	v_mfma_f32_16x16x32_bf16 v[106:109], v[182:185], v[194:197], v[106:109]
	v_mfma_f32_16x16x32_bf16 v[102:105], v[174:177], v[202:205], v[102:105]
	v_mfma_f32_16x16x32_bf16 v[98:101], v[182:185], v[202:205], v[98:101]
	v_mfma_f32_16x16x32_bf16 v[86:89], v[174:177], v[218:221], v[86:89]
	v_mfma_f32_16x16x32_bf16 v[82:85], v[182:185], v[218:221], v[82:85]
	v_mfma_f32_16x16x32_bf16 v[70:73], v[174:177], v[230:233], v[70:73]
	v_mfma_f32_16x16x32_bf16 v[66:69], v[182:185], v[230:233], v[66:69]
	s_setprio 0
	s_barrier
	s_add_i32 s28, s58, s34
	v_lshl_add_u64 v[132:133], v[132:133], 0, s[20:21]
	s_mov_b32 m0, s28
	ds_read_b128 v[186:189], v152 offset:49152
	ds_read_b128 v[194:197], v152 offset:50176
	ds_read_b128 v[198:201], v152 offset:51200
	ds_read_b128 v[202:205], v152 offset:52224
	ds_read_b128 v[206:209], v152 offset:53248
	ds_read_b128 v[218:221], v152 offset:54272
	ds_read_b128 v[226:229], v152 offset:55296
	ds_read_b128 v[230:233], v152 offset:56320
	global_load_lds_dwordx4 v[132:133], off
	v_lshl_add_u64 v[132:133], v[190:191], 0, s[20:21]
	s_add_i32 m0, s28, 0x2000
	s_add_i32 s28, s59, s34
	global_load_lds_dwordx4 v[132:133], off
	v_lshl_add_u64 v[132:133], v[210:211], 0, s[20:21]
	s_mov_b32 m0, s28
	s_nop 0
	global_load_lds_dwordx4 v[132:133], off
	v_lshl_add_u64 v[132:133], v[234:235], 0, s[20:21]
	s_add_i32 m0, s28, 0x2000
	s_nop 0
	global_load_lds_dwordx4 v[132:133], off
	v_lshl_add_u64 v[132:133], v[236:237], 0, s[20:21]
	s_mov_b32 m0, s42
	s_nop 0
	global_load_lds_dwordx4 v[132:133], off
	v_lshl_add_u64 v[132:133], v[238:239], 0, s[20:21]
	s_mov_b32 m0, s43
	s_nop 0
	global_load_lds_dwordx4 v[132:133], off
	s_waitcnt vmcnt(8)
	s_waitcnt lgkmcnt(0)
	s_barrier
	s_setprio 1
	s_waitcnt lgkmcnt(0)
	v_mfma_f32_16x16x32_bf16 v[62:65], v[154:157], v[186:189], v[62:65]
	v_mfma_f32_16x16x32_bf16 v[58:61], v[162:165], v[186:189], v[58:61]
	v_mfma_f32_16x16x32_bf16 v[46:49], v[154:157], v[198:201], v[46:49]
	v_mfma_f32_16x16x32_bf16 v[42:45], v[162:165], v[198:201], v[42:45]
	v_mfma_f32_16x16x32_bf16 v[30:33], v[154:157], v[206:209], v[30:33]
	v_mfma_f32_16x16x32_bf16 v[26:29], v[162:165], v[206:209], v[26:29]
	v_mfma_f32_16x16x32_bf16 v[14:17], v[154:157], v[226:229], v[14:17]
	v_mfma_f32_16x16x32_bf16 v[10:13], v[162:165], v[226:229], v[10:13]
	v_mfma_f32_16x16x32_bf16 v[62:65], v[158:161], v[194:197], v[62:65]
	v_mfma_f32_16x16x32_bf16 v[58:61], v[166:169], v[194:197], v[58:61]
	v_mfma_f32_16x16x32_bf16 v[46:49], v[158:161], v[202:205], v[46:49]
	v_mfma_f32_16x16x32_bf16 v[42:45], v[166:169], v[202:205], v[42:45]
	v_mfma_f32_16x16x32_bf16 v[30:33], v[158:161], v[218:221], v[30:33]
	v_mfma_f32_16x16x32_bf16 v[26:29], v[166:169], v[218:221], v[26:29]
	v_mfma_f32_16x16x32_bf16 v[14:17], v[158:161], v[230:233], v[14:17]
	v_mfma_f32_16x16x32_bf16 v[10:13], v[166:169], v[230:233], v[10:13]
	v_mfma_f32_16x16x32_bf16 v[54:57], v[170:173], v[186:189], v[54:57]
	v_mfma_f32_16x16x32_bf16 v[50:53], v[178:181], v[186:189], v[50:53]
	v_mfma_f32_16x16x32_bf16 v[38:41], v[170:173], v[198:201], v[38:41]
	v_mfma_f32_16x16x32_bf16 v[34:37], v[178:181], v[198:201], v[34:37]
	v_mfma_f32_16x16x32_bf16 v[22:25], v[170:173], v[206:209], v[22:25]
	v_mfma_f32_16x16x32_bf16 v[18:21], v[178:181], v[206:209], v[18:21]
	v_mfma_f32_16x16x32_bf16 v[6:9], v[170:173], v[226:229], v[6:9]
	v_mfma_f32_16x16x32_bf16 v[2:5], v[178:181], v[226:229], v[2:5]
	v_mfma_f32_16x16x32_bf16 v[54:57], v[174:177], v[194:197], v[54:57]
	v_mfma_f32_16x16x32_bf16 v[50:53], v[182:185], v[194:197], v[50:53]
	v_mfma_f32_16x16x32_bf16 v[38:41], v[174:177], v[202:205], v[38:41]
	v_mfma_f32_16x16x32_bf16 v[34:37], v[182:185], v[202:205], v[34:37]
	v_mfma_f32_16x16x32_bf16 v[22:25], v[174:177], v[218:221], v[22:25]
	v_mfma_f32_16x16x32_bf16 v[18:21], v[182:185], v[218:221], v[18:21]
	v_mfma_f32_16x16x32_bf16 v[6:9], v[174:177], v[230:233], v[6:9]
	v_mfma_f32_16x16x32_bf16 v[2:5], v[182:185], v[230:233], v[2:5]
	s_setprio 0
	s_barrier
	s_add_u32 s26, s26, 0x100
	s_addc_u32 s27, s27, 0
	s_add_u32 s53, s53, 0x100
	s_addc_u32 s54, s54, 0
	s_cmp_ge_i32 s55, s45
	s_mov_b32 s28, s55
	s_cbranch_scc0 .LBB0_1864
